# d4 + MFMA order with no operand shared between consecutive MFMAs (7 loops, phase-6 loop untouched)
# baseline (speedup 1.0000x reference)
; #define PG8_STAGE(bufoff, gbase, voff) do { _Pragma("unroll") for (int _i = 0; _i < 2; ++_i) \
;         __builtin_amdgcn_global_load_lds((const unsigned*)((const char*)(gbase) + (voff)[_i]), (LAS unsigned*)(lds + (bufoff) + ldsw + _i * 8192), 16, 0, 0); } while (0)
; #define PG8_LDA(dst, b, h) do { _Pragma("unroll") for (int m = 0; m < 4; ++m) _Pragma("unroll") for (int k = 0; k < 2; ++k) dst[m][k] = *(const LAS bf16x8*)(lds + PG8_SA(b, h) + aoff + m * 2048 + k * 1024); } while (0)
; #define PG8_LDB(dst, b, h) do { _Pragma("unroll") for (int n = 0; n < 2; ++n) _Pragma("unroll") for (int k = 0; k < 2; ++k) dst[n][k] = *(const LAS bf16x8*)(lds + PG8_SB(b, h) + boff + n * 2048 + k * 1024); } while (0)
; #define PG8_MMA(ai, bj, At, Bt) do { __builtin_amdgcn_s_setprio(1); _Pragma("unroll") for (int m = 0; m < 4; ++m) _Pragma("unroll") for (int n = 0; n < 2; ++n) _Pragma("unroll") for (int k = 0; k < 2; ++k) \
;         acc[ai][bj][m][n] = __builtin_amdgcn_mfma_f32_16x16x32_bf16(Bt[n][k], At[m][k], acc[ai][bj][m][n], 0, 0, 0); __builtin_amdgcn_s_setprio(0); } while (0)
; #define PG8_WAIT_V(n) asm volatile("s_waitcnt vmcnt(" #n ")" ::: "memory")
; #define PG8_WAIT_L(n) asm volatile("s_waitcnt lgkmcnt(" #n ")" ::: "memory")
; #define PG8_BAR __builtin_amdgcn_s_barrier()
; template <class Epi>
; __device__ __forceinline__ void gemm_phase(LAS unsigned char* lds, const Gemm g, const StaticOrder& S, const Epi& E) {
;     ...
;             const bool last = (t == nt - 2);
;             const char* a1 = cA + (size_t)(t + 1) * kstep;
;             const char* a2 = last ? nA : cA + (size_t)(t + 2) * kstep; const char* b2 = last ? nB : cB + (size_t)(t + 2) * kstep;
;             const char* a3 = a2 + kstep; const char* b3 = b2 + kstep;
;             if constexpr (Epi::MIDK > 0) { if (t == Epi::MIDK) E.mid(acc, cur, wr, wc, fr, fq); }
;             PG8_LDB(B0, 0, 0); PG8_LDB(B1, 0, 1); PG8_SCHED; PG8_LDA(At, 0, 0); PG8_STAGE(PG8_SA(1, 1), a1 + hstep, voffA);
;             PG8_WAIT_V(8); PG8_WAIT_L(0); PG8_BAR; PG8_MMA(0, 0, At, B0); PG8_MMA(0, 1, At, B1); PG8_BAR; PG8_SCHED;
;             PG8_LDA(At, 0, 1); PG8_STAGE(PG8_SB(0, 0), b2, voffB); PG8_STAGE(PG8_SB(0, 1), b2 + hstep, voffB); PG8_STAGE(PG8_SA(0, 0), a2, voffA);
;             PG8_WAIT_V(8); PG8_WAIT_L(0); PG8_BAR; PG8_MMA(1, 0, At, B0); PG8_MMA(1, 1, At, B1); PG8_BAR; PG8_SCHED;
.LBB0_134:
	ds_read_b128 v[158:161], v150
	ds_read_b128 v[162:165], v150 offset:1024
	ds_read_b128 v[166:169], v150 offset:2048
	ds_read_b128 v[174:177], v150 offset:3072
	ds_read_b128 v[178:181], v151
	ds_read_b128 v[182:185], v151 offset:1024
	ds_read_b128 v[186:189], v151 offset:2048
	ds_read_b128 v[190:193], v151 offset:3072
	s_add_u32 s66, s64, 0xfffc0080
	s_addc_u32 s67, s65, -1
	s_cmp_eq_u32 s92, 12
	s_cselect_b32 s69, s87, s67
	s_cselect_b32 s68, s88, s66
	s_cselect_b32 s67, s47, s91
	s_cselect_b32 s66, s89, s90
	s_add_i32 m0, s61, 0xc000
	ds_read_b128 v[194:197], v152
	ds_read_b128 v[198:201], v152 offset:1024
	ds_read_b128 v[202:205], v152 offset:2048
	ds_read_b128 v[206:209], v152 offset:3072
	ds_read_b128 v[210:213], v152 offset:4096
	ds_read_b128 v[214:217], v152 offset:5120
	ds_read_b128 v[218:221], v152 offset:6144
	ds_read_b128 v[222:225], v152 offset:7168
	global_load_lds_dwordx4 v140, s[64:65]
	s_add_i32 m0, s61, 0xe000
	s_nop 0
	global_load_lds_dwordx4 v142, s[64:65]
	s_waitcnt vmcnt(8)
	s_waitcnt lgkmcnt(0)
	s_setprio 1
	s_barrier
	v_mfma_f32_16x16x32_bf16 v[126:129], v[158:161], v[194:197], v[126:129]
	v_mfma_f32_16x16x32_bf16 v[102:105], v[166:169], v[202:205], v[102:105]
	v_mfma_f32_16x16x32_bf16 v[94:97], v[158:161], v[210:213], v[94:97]
	v_mfma_f32_16x16x32_bf16 v[70:73], v[166:169], v[218:221], v[70:73]
	v_mfma_f32_16x16x32_bf16 v[118:121], v[166:169], v[194:197], v[118:121]
	v_mfma_f32_16x16x32_bf16 v[110:113], v[158:161], v[202:205], v[110:113]
	v_mfma_f32_16x16x32_bf16 v[86:89], v[166:169], v[210:213], v[86:89]
	v_mfma_f32_16x16x32_bf16 v[78:81], v[158:161], v[218:221], v[78:81]
	v_mfma_f32_16x16x32_bf16 v[126:129], v[162:165], v[198:201], v[126:129]
	v_mfma_f32_16x16x32_bf16 v[102:105], v[174:177], v[206:209], v[102:105]
	v_mfma_f32_16x16x32_bf16 v[94:97], v[162:165], v[214:217], v[94:97]
	v_mfma_f32_16x16x32_bf16 v[70:73], v[174:177], v[222:225], v[70:73]
	v_mfma_f32_16x16x32_bf16 v[118:121], v[174:177], v[198:201], v[118:121]
	v_mfma_f32_16x16x32_bf16 v[110:113], v[162:165], v[206:209], v[110:113]
	v_mfma_f32_16x16x32_bf16 v[86:89], v[174:177], v[214:217], v[86:89]
	v_mfma_f32_16x16x32_bf16 v[78:81], v[162:165], v[222:225], v[78:81]
	v_mfma_f32_16x16x32_bf16 v[122:125], v[178:181], v[194:197], v[122:125]
	v_mfma_f32_16x16x32_bf16 v[98:101], v[186:189], v[202:205], v[98:101]
	v_mfma_f32_16x16x32_bf16 v[90:93], v[178:181], v[210:213], v[90:93]
	v_mfma_f32_16x16x32_bf16 v[66:69], v[186:189], v[218:221], v[66:69]
	v_mfma_f32_16x16x32_bf16 v[114:117], v[186:189], v[194:197], v[114:117]
	v_mfma_f32_16x16x32_bf16 v[106:109], v[178:181], v[202:205], v[106:109]
	v_mfma_f32_16x16x32_bf16 v[82:85], v[186:189], v[210:213], v[82:85]
	v_mfma_f32_16x16x32_bf16 v[74:77], v[178:181], v[218:221], v[74:77]
	v_mfma_f32_16x16x32_bf16 v[122:125], v[182:185], v[198:201], v[122:125]
	v_mfma_f32_16x16x32_bf16 v[98:101], v[190:193], v[206:209], v[98:101]
	v_mfma_f32_16x16x32_bf16 v[90:93], v[182:185], v[214:217], v[90:93]
	v_mfma_f32_16x16x32_bf16 v[66:69], v[190:193], v[222:225], v[66:69]
	v_mfma_f32_16x16x32_bf16 v[114:117], v[190:193], v[198:201], v[114:117]
	v_mfma_f32_16x16x32_bf16 v[106:109], v[182:185], v[206:209], v[106:109]
	v_mfma_f32_16x16x32_bf16 v[82:85], v[190:193], v[214:217], v[82:85]
	v_mfma_f32_16x16x32_bf16 v[74:77], v[182:185], v[222:225], v[74:77]
	s_barrier
	s_setprio 0
	s_add_u32 s98, s66, s8
	s_addc_u32 s99, s67, s9
	s_add_u32 s100, s68, s8
	s_addc_u32 s101, s69, s9
	s_add_i32 s93, s83, s6
	s_mov_b32 m0, s93
	ds_read_b128 v[194:197], v152 offset:16384
	ds_read_b128 v[198:201], v152 offset:17408
	ds_read_b128 v[202:205], v152 offset:18432
	ds_read_b128 v[206:209], v152 offset:19456
	ds_read_b128 v[210:213], v152 offset:20480
	ds_read_b128 v[214:217], v152 offset:21504
	ds_read_b128 v[218:221], v152 offset:22528
	ds_read_b128 v[222:225], v152 offset:23552
	global_load_lds_dwordx4 v132, s[66:67]
	s_add_i32 m0, s93, 0x2000
	s_add_u32 s94, s66, 0x40000
	s_addc_u32 s95, s67, 0
	s_add_i32 s93, s84, s6
	global_load_lds_dwordx4 v136, s[66:67]
	s_mov_b32 m0, s93
	s_nop 0
	global_load_lds_dwordx4 v132, s[94:95]
	s_add_i32 m0, s93, 0x2000
	s_nop 0
	global_load_lds_dwordx4 v136, s[94:95]
	s_mov_b32 m0, s61
	s_nop 0
	global_load_lds_dwordx4 v130, s[68:69]
	s_mov_b32 m0, s63
	s_nop 0
	global_load_lds_dwordx4 v134, s[68:69]
	s_waitcnt vmcnt(8)
	s_waitcnt lgkmcnt(0)
	s_setprio 1
	s_barrier
	v_mfma_f32_16x16x32_bf16 v[62:65], v[158:161], v[194:197], v[62:65]
	v_mfma_f32_16x16x32_bf16 v[38:41], v[166:169], v[202:205], v[38:41]
	v_mfma_f32_16x16x32_bf16 v[30:33], v[158:161], v[210:213], v[30:33]
	v_mfma_f32_16x16x32_bf16 v[6:9], v[166:169], v[218:221], v[6:9]
	v_mfma_f32_16x16x32_bf16 v[54:57], v[166:169], v[194:197], v[54:57]
	v_mfma_f32_16x16x32_bf16 v[46:49], v[158:161], v[202:205], v[46:49]
	v_mfma_f32_16x16x32_bf16 v[22:25], v[166:169], v[210:213], v[22:25]
	v_mfma_f32_16x16x32_bf16 v[14:17], v[158:161], v[218:221], v[14:17]
	v_mfma_f32_16x16x32_bf16 v[62:65], v[162:165], v[198:201], v[62:65]
	v_mfma_f32_16x16x32_bf16 v[38:41], v[174:177], v[206:209], v[38:41]
	v_mfma_f32_16x16x32_bf16 v[30:33], v[162:165], v[214:217], v[30:33]
	v_mfma_f32_16x16x32_bf16 v[6:9], v[174:177], v[222:225], v[6:9]
	v_mfma_f32_16x16x32_bf16 v[54:57], v[174:177], v[198:201], v[54:57]
	v_mfma_f32_16x16x32_bf16 v[46:49], v[162:165], v[206:209], v[46:49]
	v_mfma_f32_16x16x32_bf16 v[22:25], v[174:177], v[214:217], v[22:25]
	v_mfma_f32_16x16x32_bf16 v[14:17], v[162:165], v[222:225], v[14:17]
	v_mfma_f32_16x16x32_bf16 v[58:61], v[178:181], v[194:197], v[58:61]
	v_mfma_f32_16x16x32_bf16 v[34:37], v[186:189], v[202:205], v[34:37]
	v_mfma_f32_16x16x32_bf16 v[26:29], v[178:181], v[210:213], v[26:29]
	v_mfma_f32_16x16x32_bf16 v[2:5], v[186:189], v[218:221], v[2:5]
	v_mfma_f32_16x16x32_bf16 v[50:53], v[186:189], v[194:197], v[50:53]
	v_mfma_f32_16x16x32_bf16 v[42:45], v[178:181], v[202:205], v[42:45]
	v_mfma_f32_16x16x32_bf16 v[18:21], v[186:189], v[210:213], v[18:21]
	v_mfma_f32_16x16x32_bf16 v[10:13], v[178:181], v[218:221], v[10:13]
	v_mfma_f32_16x16x32_bf16 v[58:61], v[182:185], v[198:201], v[58:61]
	v_mfma_f32_16x16x32_bf16 v[34:37], v[190:193], v[206:209], v[34:37]
	v_mfma_f32_16x16x32_bf16 v[26:29], v[182:185], v[214:217], v[26:29]
	v_mfma_f32_16x16x32_bf16 v[2:5], v[190:193], v[222:225], v[2:5]
	v_mfma_f32_16x16x32_bf16 v[50:53], v[190:193], v[198:201], v[50:53]
	v_mfma_f32_16x16x32_bf16 v[42:45], v[182:185], v[206:209], v[42:45]
	v_mfma_f32_16x16x32_bf16 v[18:21], v[190:193], v[214:217], v[18:21]
	v_mfma_f32_16x16x32_bf16 v[10:13], v[182:185], v[222:225], v[10:13]
	s_barrier
; #define PG8_STAGE(bufoff, gbase, voff) do { _Pragma("unroll") for (int _i = 0; _i < 2; ++_i) \
;         __builtin_amdgcn_global_load_lds((const unsigned*)((const char*)(gbase) + (voff)[_i]), (LAS unsigned*)(lds + (bufoff) + ldsw + _i * 8192), 16, 0, 0); } while (0)
; #define PG8_LDA(dst, b, h) do { _Pragma("unroll") for (int m = 0; m < 4; ++m) _Pragma("unroll") for (int k = 0; k < 2; ++k) dst[m][k] = *(const LAS bf16x8*)(lds + PG8_SA(b, h) + aoff + m * 2048 + k * 1024); } while (0)
; #define PG8_LDB(dst, b, h) do { _Pragma("unroll") for (int n = 0; n < 2; ++n) _Pragma("unroll") for (int k = 0; k < 2; ++k) dst[n][k] = *(const LAS bf16x8*)(lds + PG8_SB(b, h) + boff + n * 2048 + k * 1024); } while (0)
; #define PG8_MMA(ai, bj, At, Bt) do { __builtin_amdgcn_s_setprio(1); _Pragma("unroll") for (int m = 0; m < 4; ++m) _Pragma("unroll") for (int n = 0; n < 2; ++n) _Pragma("unroll") for (int k = 0; k < 2; ++k) \
;         acc[ai][bj][m][n] = __builtin_amdgcn_mfma_f32_16x16x32_bf16(Bt[n][k], At[m][k], acc[ai][bj][m][n], 0, 0, 0); __builtin_amdgcn_s_setprio(0); } while (0)
; #define PG8_WAIT_V(n) asm volatile("s_waitcnt vmcnt(" #n ")" ::: "memory")
; #define PG8_WAIT_L(n) asm volatile("s_waitcnt lgkmcnt(" #n ")" ::: "memory")
; #define PG8_BAR __builtin_amdgcn_s_barrier()
; #define PG8_SCHED __builtin_amdgcn_sched_barrier(0)
; template <class Epi>
; __device__ __forceinline__ void gemm_phase(LAS unsigned char* lds, const Gemm g, const StaticOrder& S, const Epi& E) {
;     ...
;             PG8_LDB(B0, 1, 0); PG8_LDB(B1, 1, 1); PG8_SCHED; PG8_LDA(At, 1, 0); PG8_STAGE(PG8_SA(0, 1), a2 + hstep, voffA);
;             PG8_WAIT_V(8); PG8_WAIT_L(0); PG8_BAR; PG8_MMA(0, 0, At, B0); PG8_MMA(0, 1, At, B1); PG8_BAR; PG8_SCHED;
;             PG8_LDA(At, 1, 1); PG8_STAGE(PG8_SB(1, 0), b3, voffB); PG8_STAGE(PG8_SB(1, 1), b3 + hstep, voffB); PG8_STAGE(PG8_SA(1, 0), a3, voffA);
;             PG8_WAIT_V(8); PG8_WAIT_L(0); PG8_BAR; PG8_MMA(1, 0, At, B0); PG8_MMA(1, 1, At, B1); PG8_BAR; PG8_SCHED;
;         }
;         if (wr == 0) PG8_BAR;
	s_setprio 0
	s_add_i32 s93, 0, 0x18000
	s_add_i32 s94, 0, 0x1c000
	v_add_u32_e32 v174, s93, v148
	v_add_u32_e32 v190, s94, v148
	ds_read_b128 v[158:161], v174
	ds_read_b128 v[162:165], v174 offset:1024
	ds_read_b128 v[166:169], v174 offset:2048
	ds_read_b128 v[174:177], v174 offset:3072
	ds_read_b128 v[178:181], v190
	ds_read_b128 v[182:185], v190 offset:1024
	ds_read_b128 v[186:189], v190 offset:2048
	ds_read_b128 v[190:193], v190 offset:3072
	s_add_u32 s68, s68, 0x40000
	s_addc_u32 s69, s69, 0
	s_mov_b32 m0, s77
	ds_read_b128 v[194:197], v152 offset:32768
	ds_read_b128 v[198:201], v152 offset:33792
	ds_read_b128 v[202:205], v152 offset:34816
	ds_read_b128 v[206:209], v152 offset:35840
	ds_read_b128 v[210:213], v152 offset:36864
	ds_read_b128 v[214:217], v152 offset:37888
	ds_read_b128 v[218:221], v152 offset:38912
	ds_read_b128 v[222:225], v152 offset:39936
	global_load_lds_dwordx4 v130, s[68:69]
	s_mov_b32 m0, s78
	s_nop 0
	global_load_lds_dwordx4 v134, s[68:69]
	s_waitcnt vmcnt(8)
	s_waitcnt lgkmcnt(0)
	s_setprio 1
	s_barrier
	v_mfma_f32_16x16x32_bf16 v[126:129], v[158:161], v[194:197], v[126:129]
	v_mfma_f32_16x16x32_bf16 v[102:105], v[166:169], v[202:205], v[102:105]
	v_mfma_f32_16x16x32_bf16 v[94:97], v[158:161], v[210:213], v[94:97]
	v_mfma_f32_16x16x32_bf16 v[70:73], v[166:169], v[218:221], v[70:73]
	v_mfma_f32_16x16x32_bf16 v[118:121], v[166:169], v[194:197], v[118:121]
	v_mfma_f32_16x16x32_bf16 v[110:113], v[158:161], v[202:205], v[110:113]
	v_mfma_f32_16x16x32_bf16 v[86:89], v[166:169], v[210:213], v[86:89]
	v_mfma_f32_16x16x32_bf16 v[78:81], v[158:161], v[218:221], v[78:81]
	v_mfma_f32_16x16x32_bf16 v[126:129], v[162:165], v[198:201], v[126:129]
	v_mfma_f32_16x16x32_bf16 v[102:105], v[174:177], v[206:209], v[102:105]
	v_mfma_f32_16x16x32_bf16 v[94:97], v[162:165], v[214:217], v[94:97]
	v_mfma_f32_16x16x32_bf16 v[70:73], v[174:177], v[222:225], v[70:73]
	v_mfma_f32_16x16x32_bf16 v[118:121], v[174:177], v[198:201], v[118:121]
	v_mfma_f32_16x16x32_bf16 v[110:113], v[162:165], v[206:209], v[110:113]
	v_mfma_f32_16x16x32_bf16 v[86:89], v[174:177], v[214:217], v[86:89]
	v_mfma_f32_16x16x32_bf16 v[78:81], v[162:165], v[222:225], v[78:81]
	v_mfma_f32_16x16x32_bf16 v[122:125], v[178:181], v[194:197], v[122:125]
	v_mfma_f32_16x16x32_bf16 v[98:101], v[186:189], v[202:205], v[98:101]
	v_mfma_f32_16x16x32_bf16 v[90:93], v[178:181], v[210:213], v[90:93]
	v_mfma_f32_16x16x32_bf16 v[66:69], v[186:189], v[218:221], v[66:69]
	v_mfma_f32_16x16x32_bf16 v[114:117], v[186:189], v[194:197], v[114:117]
	v_mfma_f32_16x16x32_bf16 v[106:109], v[178:181], v[202:205], v[106:109]
	v_mfma_f32_16x16x32_bf16 v[82:85], v[186:189], v[210:213], v[82:85]
	v_mfma_f32_16x16x32_bf16 v[74:77], v[178:181], v[218:221], v[74:77]
	v_mfma_f32_16x16x32_bf16 v[122:125], v[182:185], v[198:201], v[122:125]
	v_mfma_f32_16x16x32_bf16 v[98:101], v[190:193], v[206:209], v[98:101]
	v_mfma_f32_16x16x32_bf16 v[90:93], v[182:185], v[214:217], v[90:93]
	v_mfma_f32_16x16x32_bf16 v[66:69], v[190:193], v[222:225], v[66:69]
	v_mfma_f32_16x16x32_bf16 v[114:117], v[190:193], v[198:201], v[114:117]
	v_mfma_f32_16x16x32_bf16 v[106:109], v[182:185], v[206:209], v[106:109]
	v_mfma_f32_16x16x32_bf16 v[82:85], v[190:193], v[214:217], v[82:85]
	v_mfma_f32_16x16x32_bf16 v[74:77], v[182:185], v[222:225], v[74:77]
	s_barrier
	s_setprio 0
	s_add_i32 s68, s93, s6
	s_mov_b32 m0, s68
	ds_read_b128 v[194:197], v152 offset:49152
	ds_read_b128 v[198:201], v152 offset:50176
	ds_read_b128 v[202:205], v152 offset:51200
	ds_read_b128 v[206:209], v152 offset:52224
	ds_read_b128 v[210:213], v152 offset:53248
	ds_read_b128 v[214:217], v152 offset:54272
	ds_read_b128 v[218:221], v152 offset:55296
	ds_read_b128 v[222:225], v152 offset:56320
	global_load_lds_dwordx4 v132, s[98:99]
	s_add_i32 m0, s68, 0x2000
	s_add_u32 s66, s66, 0x40080
	s_addc_u32 s67, s67, 0
	s_add_i32 s68, s94, s6
	global_load_lds_dwordx4 v136, s[98:99]
	s_mov_b32 m0, s68
	s_nop 0
	global_load_lds_dwordx4 v132, s[66:67]
	s_add_i32 m0, s68, 0x2000
	s_nop 0
	global_load_lds_dwordx4 v136, s[66:67]
	s_mov_b32 m0, s79
	s_nop 0
	global_load_lds_dwordx4 v130, s[100:101]
	s_mov_b32 m0, s80
	s_nop 0
	global_load_lds_dwordx4 v134, s[100:101]
	s_waitcnt vmcnt(8)
	s_waitcnt lgkmcnt(0)
	s_setprio 1
	s_barrier
	v_mfma_f32_16x16x32_bf16 v[62:65], v[158:161], v[194:197], v[62:65]
	v_mfma_f32_16x16x32_bf16 v[38:41], v[166:169], v[202:205], v[38:41]
	v_mfma_f32_16x16x32_bf16 v[30:33], v[158:161], v[210:213], v[30:33]
	v_mfma_f32_16x16x32_bf16 v[6:9], v[166:169], v[218:221], v[6:9]
	v_mfma_f32_16x16x32_bf16 v[54:57], v[166:169], v[194:197], v[54:57]
	v_mfma_f32_16x16x32_bf16 v[46:49], v[158:161], v[202:205], v[46:49]
	v_mfma_f32_16x16x32_bf16 v[22:25], v[166:169], v[210:213], v[22:25]
	v_mfma_f32_16x16x32_bf16 v[14:17], v[158:161], v[218:221], v[14:17]
	v_mfma_f32_16x16x32_bf16 v[62:65], v[162:165], v[198:201], v[62:65]
	v_mfma_f32_16x16x32_bf16 v[38:41], v[174:177], v[206:209], v[38:41]
	v_mfma_f32_16x16x32_bf16 v[30:33], v[162:165], v[214:217], v[30:33]
	v_mfma_f32_16x16x32_bf16 v[6:9], v[174:177], v[222:225], v[6:9]
	v_mfma_f32_16x16x32_bf16 v[54:57], v[174:177], v[198:201], v[54:57]
	v_mfma_f32_16x16x32_bf16 v[46:49], v[162:165], v[206:209], v[46:49]
	v_mfma_f32_16x16x32_bf16 v[22:25], v[174:177], v[214:217], v[22:25]
	v_mfma_f32_16x16x32_bf16 v[14:17], v[162:165], v[222:225], v[14:17]
	v_mfma_f32_16x16x32_bf16 v[58:61], v[178:181], v[194:197], v[58:61]
	v_mfma_f32_16x16x32_bf16 v[34:37], v[186:189], v[202:205], v[34:37]
	v_mfma_f32_16x16x32_bf16 v[26:29], v[178:181], v[210:213], v[26:29]
	v_mfma_f32_16x16x32_bf16 v[2:5], v[186:189], v[218:221], v[2:5]
	v_mfma_f32_16x16x32_bf16 v[50:53], v[186:189], v[194:197], v[50:53]
	v_mfma_f32_16x16x32_bf16 v[42:45], v[178:181], v[202:205], v[42:45]
	v_mfma_f32_16x16x32_bf16 v[18:21], v[186:189], v[210:213], v[18:21]
	v_mfma_f32_16x16x32_bf16 v[10:13], v[178:181], v[218:221], v[10:13]
	v_mfma_f32_16x16x32_bf16 v[58:61], v[182:185], v[198:201], v[58:61]
	v_mfma_f32_16x16x32_bf16 v[34:37], v[190:193], v[206:209], v[34:37]
	v_mfma_f32_16x16x32_bf16 v[26:29], v[182:185], v[214:217], v[26:29]
	v_mfma_f32_16x16x32_bf16 v[2:5], v[190:193], v[222:225], v[2:5]
	v_mfma_f32_16x16x32_bf16 v[50:53], v[190:193], v[198:201], v[50:53]
	v_mfma_f32_16x16x32_bf16 v[42:45], v[182:185], v[206:209], v[42:45]
	v_mfma_f32_16x16x32_bf16 v[18:21], v[190:193], v[214:217], v[18:21]
	v_mfma_f32_16x16x32_bf16 v[10:13], v[182:185], v[222:225], v[10:13]
	s_barrier
	s_setprio 0
	s_add_i32 s92, s92, 2
	s_add_u32 s64, s64, 0x100
	s_addc_u32 s65, s65, 0
	s_add_u32 s90, s90, 0x100
	s_addc_u32 s91, s91, 0
	s_cmp_gt_u32 s92, 13
	s_cbranch_scc0 .LBB0_134
	s_and_b64 vcc, exec, s[38:39]
	s_cbranch_vccz .LBB0_137
	s_barrier

; #define PG8_STAGE(bufoff, gbase, voff) do { _Pragma("unroll") for (int _i = 0; _i < 2; ++_i) \
;         __builtin_amdgcn_global_load_lds((const unsigned*)((const char*)(gbase) + (voff)[_i]), (LAS unsigned*)(lds + (bufoff) + ldsw + _i * 8192), 16, 0, 0); } while (0)
; #define PG8_LDA(dst, b, h) do { _Pragma("unroll") for (int m = 0; m < 4; ++m) _Pragma("unroll") for (int k = 0; k < 2; ++k) dst[m][k] = *(const LAS bf16x8*)(lds + PG8_SA(b, h) + aoff + m * 2048 + k * 1024); } while (0)
; #define PG8_LDB(dst, b, h) do { _Pragma("unroll") for (int n = 0; n < 2; ++n) _Pragma("unroll") for (int k = 0; k < 2; ++k) dst[n][k] = *(const LAS bf16x8*)(lds + PG8_SB(b, h) + boff + n * 2048 + k * 1024); } while (0)
; #define PG8_MMA(ai, bj, At, Bt) do { __builtin_amdgcn_s_setprio(1); _Pragma("unroll") for (int m = 0; m < 4; ++m) _Pragma("unroll") for (int n = 0; n < 2; ++n) _Pragma("unroll") for (int k = 0; k < 2; ++k) \
;         acc[ai][bj][m][n] = __builtin_amdgcn_mfma_f32_16x16x32_bf16(Bt[n][k], At[m][k], acc[ai][bj][m][n], 0, 0, 0); __builtin_amdgcn_s_setprio(0); } while (0)
; #define PG8_WAIT_V(n) asm volatile("s_waitcnt vmcnt(" #n ")" ::: "memory")
; #define PG8_WAIT_L(n) asm volatile("s_waitcnt lgkmcnt(" #n ")" ::: "memory")
; #define PG8_BAR __builtin_amdgcn_s_barrier()
; template <class Epi>
; __device__ __forceinline__ void gemm_phase(LAS unsigned char* lds, const Gemm g, const StaticOrder& S, const Epi& E) {
;     ...
;             const bool last = (t == nt - 2);
;             const char* a1 = cA + (size_t)(t + 1) * kstep;
;             const char* a2 = last ? nA : cA + (size_t)(t + 2) * kstep; const char* b2 = last ? nB : cB + (size_t)(t + 2) * kstep;
;             const char* a3 = a2 + kstep; const char* b3 = b2 + kstep;
;             if constexpr (Epi::MIDK > 0) { if (t == Epi::MIDK) E.mid(acc, cur, wr, wc, fr, fq); }
;             PG8_LDB(B0, 0, 0); PG8_LDB(B1, 0, 1); PG8_SCHED; PG8_LDA(At, 0, 0); PG8_STAGE(PG8_SA(1, 1), a1 + hstep, voffA);
;             PG8_WAIT_V(8); PG8_WAIT_L(0); PG8_BAR; PG8_MMA(0, 0, At, B0); PG8_MMA(0, 1, At, B1); PG8_BAR; PG8_SCHED;
;             PG8_LDA(At, 0, 1); PG8_STAGE(PG8_SB(0, 0), b2, voffB); PG8_STAGE(PG8_SB(0, 1), b2 + hstep, voffB); PG8_STAGE(PG8_SA(0, 0), a2, voffA);
;             PG8_WAIT_V(8); PG8_WAIT_L(0); PG8_BAR; PG8_MMA(1, 0, At, B0); PG8_MMA(1, 1, At, B1); PG8_BAR; PG8_SCHED;
.LBB0_221:
	ds_read_b128 v[130:133], v162
	ds_read_b128 v[134:137], v162 offset:1024
	ds_read_b128 v[154:157], v162 offset:2048
	ds_read_b128 v[166:169], v162 offset:3072
	ds_read_b128 v[174:177], v163
	ds_read_b128 v[178:181], v163 offset:1024
	ds_read_b128 v[182:185], v163 offset:2048
	ds_read_b128 v[186:189], v163 offset:3072
	s_add_u32 s48, s46, 0xfff50080
	s_addc_u32 s49, s47, -1
	s_cmp_eq_u32 s84, 40
	s_cselect_b32 s51, s5, s49
	s_cselect_b32 s50, s4, s48
	s_cselect_b32 s49, s45, s83
	s_cselect_b32 s48, s44, s82
	s_add_i32 m0, s59, 0xc000
	ds_read_b128 v[190:193], v164
	ds_read_b128 v[194:197], v164 offset:1024
	ds_read_b128 v[198:201], v164 offset:2048
	ds_read_b128 v[202:205], v164 offset:3072
	ds_read_b128 v[206:209], v164 offset:4096
	ds_read_b128 v[210:213], v164 offset:5120
	ds_read_b128 v[214:217], v164 offset:6144
	ds_read_b128 v[218:221], v164 offset:7168
	global_load_lds_dwordx4 v146, s[46:47]
	s_add_i32 m0, s59, 0xe000
	s_nop 0
	global_load_lds_dwordx4 v148, s[46:47]
	s_waitcnt vmcnt(8)
	s_waitcnt lgkmcnt(0)
	s_setprio 1
	s_barrier
	v_mfma_f32_16x16x32_bf16 v[126:129], v[130:133], v[190:193], v[126:129]
	v_mfma_f32_16x16x32_bf16 v[106:109], v[154:157], v[198:201], v[106:109]
	v_mfma_f32_16x16x32_bf16 v[94:97], v[130:133], v[206:209], v[94:97]
	v_mfma_f32_16x16x32_bf16 v[74:77], v[154:157], v[214:217], v[74:77]
	v_mfma_f32_16x16x32_bf16 v[122:125], v[154:157], v[190:193], v[122:125]
	v_mfma_f32_16x16x32_bf16 v[110:113], v[130:133], v[198:201], v[110:113]
	v_mfma_f32_16x16x32_bf16 v[90:93], v[154:157], v[206:209], v[90:93]
	v_mfma_f32_16x16x32_bf16 v[78:81], v[130:133], v[214:217], v[78:81]
	v_mfma_f32_16x16x32_bf16 v[126:129], v[134:137], v[194:197], v[126:129]
	v_mfma_f32_16x16x32_bf16 v[106:109], v[166:169], v[202:205], v[106:109]
	v_mfma_f32_16x16x32_bf16 v[94:97], v[134:137], v[210:213], v[94:97]
	v_mfma_f32_16x16x32_bf16 v[74:77], v[166:169], v[218:221], v[74:77]
	v_mfma_f32_16x16x32_bf16 v[122:125], v[166:169], v[194:197], v[122:125]
	v_mfma_f32_16x16x32_bf16 v[110:113], v[134:137], v[202:205], v[110:113]
	v_mfma_f32_16x16x32_bf16 v[90:93], v[166:169], v[210:213], v[90:93]
	v_mfma_f32_16x16x32_bf16 v[78:81], v[134:137], v[218:221], v[78:81]
	v_mfma_f32_16x16x32_bf16 v[118:121], v[174:177], v[190:193], v[118:121]
	v_mfma_f32_16x16x32_bf16 v[98:101], v[182:185], v[198:201], v[98:101]
	v_mfma_f32_16x16x32_bf16 v[86:89], v[174:177], v[206:209], v[86:89]
	v_mfma_f32_16x16x32_bf16 v[66:69], v[182:185], v[214:217], v[66:69]
	v_mfma_f32_16x16x32_bf16 v[114:117], v[182:185], v[190:193], v[114:117]
	v_mfma_f32_16x16x32_bf16 v[102:105], v[174:177], v[198:201], v[102:105]
	v_mfma_f32_16x16x32_bf16 v[82:85], v[182:185], v[206:209], v[82:85]
	v_mfma_f32_16x16x32_bf16 v[70:73], v[174:177], v[214:217], v[70:73]
	v_mfma_f32_16x16x32_bf16 v[118:121], v[178:181], v[194:197], v[118:121]
	v_mfma_f32_16x16x32_bf16 v[98:101], v[186:189], v[202:205], v[98:101]
	v_mfma_f32_16x16x32_bf16 v[86:89], v[178:181], v[210:213], v[86:89]
	v_mfma_f32_16x16x32_bf16 v[66:69], v[186:189], v[218:221], v[66:69]
	v_mfma_f32_16x16x32_bf16 v[114:117], v[186:189], v[194:197], v[114:117]
	v_mfma_f32_16x16x32_bf16 v[102:105], v[178:181], v[202:205], v[102:105]
	v_mfma_f32_16x16x32_bf16 v[82:85], v[186:189], v[210:213], v[82:85]
	v_mfma_f32_16x16x32_bf16 v[70:73], v[178:181], v[218:221], v[70:73]
	s_barrier
	s_setprio 0
	s_add_u32 s98, s48, s38
	s_addc_u32 s99, s49, s39
	s_add_u32 s100, s50, s38
	s_addc_u32 s101, s51, s39
	s_add_i32 s85, s76, s58
	s_mov_b32 m0, s85
	ds_read_b128 v[190:193], v164 offset:16384
	ds_read_b128 v[194:197], v164 offset:17408
	ds_read_b128 v[198:201], v164 offset:18432
	ds_read_b128 v[202:205], v164 offset:19456
	ds_read_b128 v[206:209], v164 offset:20480
	ds_read_b128 v[210:213], v164 offset:21504
	ds_read_b128 v[214:217], v164 offset:22528
	ds_read_b128 v[218:221], v164 offset:23552
	global_load_lds_dwordx4 v140, s[48:49]
	s_add_i32 m0, s85, 0x2000
	s_add_u32 s86, s48, 0xb0000
	s_addc_u32 s87, s49, 0
	s_add_i32 s85, s77, s58
	global_load_lds_dwordx4 v144, s[48:49]
	s_mov_b32 m0, s85
	s_nop 0
	global_load_lds_dwordx4 v140, s[86:87]
	s_add_i32 m0, s85, 0x2000
	s_nop 0
	global_load_lds_dwordx4 v144, s[86:87]
	s_mov_b32 m0, s59
	s_nop 0
	global_load_lds_dwordx4 v138, s[50:51]
	s_mov_b32 m0, s60
	s_nop 0
	global_load_lds_dwordx4 v142, s[50:51]
	s_waitcnt vmcnt(8)
	s_waitcnt lgkmcnt(0)
	s_setprio 1
	s_barrier
	v_mfma_f32_16x16x32_bf16 v[62:65], v[130:133], v[190:193], v[62:65]
	v_mfma_f32_16x16x32_bf16 v[42:45], v[154:157], v[198:201], v[42:45]
	v_mfma_f32_16x16x32_bf16 v[30:33], v[130:133], v[206:209], v[30:33]
	v_mfma_f32_16x16x32_bf16 v[10:13], v[154:157], v[214:217], v[10:13]
	v_mfma_f32_16x16x32_bf16 v[58:61], v[154:157], v[190:193], v[58:61]
	v_mfma_f32_16x16x32_bf16 v[46:49], v[130:133], v[198:201], v[46:49]
	v_mfma_f32_16x16x32_bf16 v[26:29], v[154:157], v[206:209], v[26:29]
	v_mfma_f32_16x16x32_bf16 v[14:17], v[130:133], v[214:217], v[14:17]
	v_mfma_f32_16x16x32_bf16 v[62:65], v[134:137], v[194:197], v[62:65]
	v_mfma_f32_16x16x32_bf16 v[42:45], v[166:169], v[202:205], v[42:45]
	v_mfma_f32_16x16x32_bf16 v[30:33], v[134:137], v[210:213], v[30:33]
	v_mfma_f32_16x16x32_bf16 v[10:13], v[166:169], v[218:221], v[10:13]
	v_mfma_f32_16x16x32_bf16 v[58:61], v[166:169], v[194:197], v[58:61]
	v_mfma_f32_16x16x32_bf16 v[46:49], v[134:137], v[202:205], v[46:49]
	v_mfma_f32_16x16x32_bf16 v[26:29], v[166:169], v[210:213], v[26:29]
	v_mfma_f32_16x16x32_bf16 v[14:17], v[134:137], v[218:221], v[14:17]
	v_mfma_f32_16x16x32_bf16 v[54:57], v[174:177], v[190:193], v[54:57]
	v_mfma_f32_16x16x32_bf16 v[34:37], v[182:185], v[198:201], v[34:37]
	v_mfma_f32_16x16x32_bf16 v[22:25], v[174:177], v[206:209], v[22:25]
	v_mfma_f32_16x16x32_bf16 v[2:5], v[182:185], v[214:217], v[2:5]
	v_mfma_f32_16x16x32_bf16 v[50:53], v[182:185], v[190:193], v[50:53]
	v_mfma_f32_16x16x32_bf16 v[38:41], v[174:177], v[198:201], v[38:41]
	v_mfma_f32_16x16x32_bf16 v[18:21], v[182:185], v[206:209], v[18:21]
	v_mfma_f32_16x16x32_bf16 v[6:9], v[174:177], v[214:217], v[6:9]
	v_mfma_f32_16x16x32_bf16 v[54:57], v[178:181], v[194:197], v[54:57]
	v_mfma_f32_16x16x32_bf16 v[34:37], v[186:189], v[202:205], v[34:37]
	v_mfma_f32_16x16x32_bf16 v[22:25], v[178:181], v[210:213], v[22:25]
	v_mfma_f32_16x16x32_bf16 v[2:5], v[186:189], v[218:221], v[2:5]
	v_mfma_f32_16x16x32_bf16 v[50:53], v[186:189], v[194:197], v[50:53]
	v_mfma_f32_16x16x32_bf16 v[38:41], v[178:181], v[202:205], v[38:41]
	v_mfma_f32_16x16x32_bf16 v[18:21], v[186:189], v[210:213], v[18:21]
	v_mfma_f32_16x16x32_bf16 v[6:9], v[178:181], v[218:221], v[6:9]
	s_barrier
; #define PG8_STAGE(bufoff, gbase, voff) do { _Pragma("unroll") for (int _i = 0; _i < 2; ++_i) \
;         __builtin_amdgcn_global_load_lds((const unsigned*)((const char*)(gbase) + (voff)[_i]), (LAS unsigned*)(lds + (bufoff) + ldsw + _i * 8192), 16, 0, 0); } while (0)
; #define PG8_LDA(dst, b, h) do { _Pragma("unroll") for (int m = 0; m < 4; ++m) _Pragma("unroll") for (int k = 0; k < 2; ++k) dst[m][k] = *(const LAS bf16x8*)(lds + PG8_SA(b, h) + aoff + m * 2048 + k * 1024); } while (0)
; #define PG8_LDB(dst, b, h) do { _Pragma("unroll") for (int n = 0; n < 2; ++n) _Pragma("unroll") for (int k = 0; k < 2; ++k) dst[n][k] = *(const LAS bf16x8*)(lds + PG8_SB(b, h) + boff + n * 2048 + k * 1024); } while (0)
; #define PG8_MMA(ai, bj, At, Bt) do { __builtin_amdgcn_s_setprio(1); _Pragma("unroll") for (int m = 0; m < 4; ++m) _Pragma("unroll") for (int n = 0; n < 2; ++n) _Pragma("unroll") for (int k = 0; k < 2; ++k) \
;         acc[ai][bj][m][n] = __builtin_amdgcn_mfma_f32_16x16x32_bf16(Bt[n][k], At[m][k], acc[ai][bj][m][n], 0, 0, 0); __builtin_amdgcn_s_setprio(0); } while (0)
; #define PG8_WAIT_V(n) asm volatile("s_waitcnt vmcnt(" #n ")" ::: "memory")
; #define PG8_WAIT_L(n) asm volatile("s_waitcnt lgkmcnt(" #n ")" ::: "memory")
; #define PG8_BAR __builtin_amdgcn_s_barrier()
; #define PG8_SCHED __builtin_amdgcn_sched_barrier(0)
; template <class Epi>
; __device__ __forceinline__ void gemm_phase(LAS unsigned char* lds, const Gemm g, const StaticOrder& S, const Epi& E) {
;     ...
;             PG8_LDB(B0, 1, 0); PG8_LDB(B1, 1, 1); PG8_SCHED; PG8_LDA(At, 1, 0); PG8_STAGE(PG8_SA(0, 1), a2 + hstep, voffA);
;             PG8_WAIT_V(8); PG8_WAIT_L(0); PG8_BAR; PG8_MMA(0, 0, At, B0); PG8_MMA(0, 1, At, B1); PG8_BAR; PG8_SCHED;
;             PG8_LDA(At, 1, 1); PG8_STAGE(PG8_SB(1, 0), b3, voffB); PG8_STAGE(PG8_SB(1, 1), b3 + hstep, voffB); PG8_STAGE(PG8_SA(1, 0), a3, voffA);
;             PG8_WAIT_V(8); PG8_WAIT_L(0); PG8_BAR; PG8_MMA(1, 0, At, B0); PG8_MMA(1, 1, At, B1); PG8_BAR; PG8_SCHED;
;         }
;         if (wr == 0) PG8_BAR;
	s_setprio 0
	s_add_i32 s85, 0, 0x18000
	s_add_i32 s86, 0, 0x1c000
	v_add_u32_e32 v166, s85, v160
	v_add_u32_e32 v186, s86, v160
	ds_read_b128 v[130:133], v166
	ds_read_b128 v[134:137], v166 offset:1024
	ds_read_b128 v[154:157], v166 offset:2048
	ds_read_b128 v[166:169], v166 offset:3072
	ds_read_b128 v[174:177], v186
	ds_read_b128 v[178:181], v186 offset:1024
	ds_read_b128 v[182:185], v186 offset:2048
	ds_read_b128 v[186:189], v186 offset:3072
	s_add_u32 s50, s50, 0xb0000
	s_addc_u32 s51, s51, 0
	s_mov_b32 m0, s61
	ds_read_b128 v[190:193], v164 offset:32768
	ds_read_b128 v[194:197], v164 offset:33792
	ds_read_b128 v[198:201], v164 offset:34816
	ds_read_b128 v[202:205], v164 offset:35840
	ds_read_b128 v[206:209], v164 offset:36864
	ds_read_b128 v[210:213], v164 offset:37888
	ds_read_b128 v[214:217], v164 offset:38912
	ds_read_b128 v[218:221], v164 offset:39936
	global_load_lds_dwordx4 v138, s[50:51]
	s_mov_b32 m0, s62
	s_nop 0
	global_load_lds_dwordx4 v142, s[50:51]
	s_waitcnt vmcnt(8)
	s_waitcnt lgkmcnt(0)
	s_setprio 1
	s_barrier
	v_mfma_f32_16x16x32_bf16 v[126:129], v[130:133], v[190:193], v[126:129]
	v_mfma_f32_16x16x32_bf16 v[106:109], v[154:157], v[198:201], v[106:109]
	v_mfma_f32_16x16x32_bf16 v[94:97], v[130:133], v[206:209], v[94:97]
	v_mfma_f32_16x16x32_bf16 v[74:77], v[154:157], v[214:217], v[74:77]
	v_mfma_f32_16x16x32_bf16 v[122:125], v[154:157], v[190:193], v[122:125]
	v_mfma_f32_16x16x32_bf16 v[110:113], v[130:133], v[198:201], v[110:113]
	v_mfma_f32_16x16x32_bf16 v[90:93], v[154:157], v[206:209], v[90:93]
	v_mfma_f32_16x16x32_bf16 v[78:81], v[130:133], v[214:217], v[78:81]
	v_mfma_f32_16x16x32_bf16 v[126:129], v[134:137], v[194:197], v[126:129]
	v_mfma_f32_16x16x32_bf16 v[106:109], v[166:169], v[202:205], v[106:109]
	v_mfma_f32_16x16x32_bf16 v[94:97], v[134:137], v[210:213], v[94:97]
	v_mfma_f32_16x16x32_bf16 v[74:77], v[166:169], v[218:221], v[74:77]
	v_mfma_f32_16x16x32_bf16 v[122:125], v[166:169], v[194:197], v[122:125]
	v_mfma_f32_16x16x32_bf16 v[110:113], v[134:137], v[202:205], v[110:113]
	v_mfma_f32_16x16x32_bf16 v[90:93], v[166:169], v[210:213], v[90:93]
	v_mfma_f32_16x16x32_bf16 v[78:81], v[134:137], v[218:221], v[78:81]
	v_mfma_f32_16x16x32_bf16 v[118:121], v[174:177], v[190:193], v[118:121]
	v_mfma_f32_16x16x32_bf16 v[98:101], v[182:185], v[198:201], v[98:101]
	v_mfma_f32_16x16x32_bf16 v[86:89], v[174:177], v[206:209], v[86:89]
	v_mfma_f32_16x16x32_bf16 v[66:69], v[182:185], v[214:217], v[66:69]
	v_mfma_f32_16x16x32_bf16 v[114:117], v[182:185], v[190:193], v[114:117]
	v_mfma_f32_16x16x32_bf16 v[102:105], v[174:177], v[198:201], v[102:105]
	v_mfma_f32_16x16x32_bf16 v[82:85], v[182:185], v[206:209], v[82:85]
	v_mfma_f32_16x16x32_bf16 v[70:73], v[174:177], v[214:217], v[70:73]
	v_mfma_f32_16x16x32_bf16 v[118:121], v[178:181], v[194:197], v[118:121]
	v_mfma_f32_16x16x32_bf16 v[98:101], v[186:189], v[202:205], v[98:101]
	v_mfma_f32_16x16x32_bf16 v[86:89], v[178:181], v[210:213], v[86:89]
	v_mfma_f32_16x16x32_bf16 v[66:69], v[186:189], v[218:221], v[66:69]
	v_mfma_f32_16x16x32_bf16 v[114:117], v[186:189], v[194:197], v[114:117]
	v_mfma_f32_16x16x32_bf16 v[102:105], v[178:181], v[202:205], v[102:105]
	v_mfma_f32_16x16x32_bf16 v[82:85], v[186:189], v[210:213], v[82:85]
	v_mfma_f32_16x16x32_bf16 v[70:73], v[178:181], v[218:221], v[70:73]
	s_barrier
	s_setprio 0
	s_add_i32 s50, s85, s58
	s_mov_b32 m0, s50
	ds_read_b128 v[190:193], v164 offset:49152
	ds_read_b128 v[194:197], v164 offset:50176
	ds_read_b128 v[198:201], v164 offset:51200
	ds_read_b128 v[202:205], v164 offset:52224
	ds_read_b128 v[206:209], v164 offset:53248
	ds_read_b128 v[210:213], v164 offset:54272
	ds_read_b128 v[214:217], v164 offset:55296
	ds_read_b128 v[218:221], v164 offset:56320
	global_load_lds_dwordx4 v140, s[98:99]
	s_add_i32 m0, s50, 0x2000
	s_add_u32 s48, s48, 0xb0080
	s_addc_u32 s49, s49, 0
	s_add_i32 s50, s86, s58
	global_load_lds_dwordx4 v144, s[98:99]
	s_mov_b32 m0, s50
	s_nop 0
	global_load_lds_dwordx4 v140, s[48:49]
	s_add_i32 m0, s50, 0x2000
	s_nop 0
	global_load_lds_dwordx4 v144, s[48:49]
	s_mov_b32 m0, s64
	s_nop 0
	global_load_lds_dwordx4 v138, s[100:101]
	s_mov_b32 m0, s65
	s_nop 0
	global_load_lds_dwordx4 v142, s[100:101]
	s_waitcnt vmcnt(8)
	s_waitcnt lgkmcnt(0)
	s_setprio 1
	s_barrier
	v_mfma_f32_16x16x32_bf16 v[62:65], v[130:133], v[190:193], v[62:65]
	v_mfma_f32_16x16x32_bf16 v[42:45], v[154:157], v[198:201], v[42:45]
	v_mfma_f32_16x16x32_bf16 v[30:33], v[130:133], v[206:209], v[30:33]
	v_mfma_f32_16x16x32_bf16 v[10:13], v[154:157], v[214:217], v[10:13]
	v_mfma_f32_16x16x32_bf16 v[58:61], v[154:157], v[190:193], v[58:61]
	v_mfma_f32_16x16x32_bf16 v[46:49], v[130:133], v[198:201], v[46:49]
	v_mfma_f32_16x16x32_bf16 v[26:29], v[154:157], v[206:209], v[26:29]
	v_mfma_f32_16x16x32_bf16 v[14:17], v[130:133], v[214:217], v[14:17]
	v_mfma_f32_16x16x32_bf16 v[62:65], v[134:137], v[194:197], v[62:65]
	v_mfma_f32_16x16x32_bf16 v[42:45], v[166:169], v[202:205], v[42:45]
	v_mfma_f32_16x16x32_bf16 v[30:33], v[134:137], v[210:213], v[30:33]
	v_mfma_f32_16x16x32_bf16 v[10:13], v[166:169], v[218:221], v[10:13]
	v_mfma_f32_16x16x32_bf16 v[58:61], v[166:169], v[194:197], v[58:61]
	v_mfma_f32_16x16x32_bf16 v[46:49], v[134:137], v[202:205], v[46:49]
	v_mfma_f32_16x16x32_bf16 v[26:29], v[166:169], v[210:213], v[26:29]
	v_mfma_f32_16x16x32_bf16 v[14:17], v[134:137], v[218:221], v[14:17]
	v_mfma_f32_16x16x32_bf16 v[54:57], v[174:177], v[190:193], v[54:57]
	v_mfma_f32_16x16x32_bf16 v[34:37], v[182:185], v[198:201], v[34:37]
	v_mfma_f32_16x16x32_bf16 v[22:25], v[174:177], v[206:209], v[22:25]
	v_mfma_f32_16x16x32_bf16 v[2:5], v[182:185], v[214:217], v[2:5]
	v_mfma_f32_16x16x32_bf16 v[50:53], v[182:185], v[190:193], v[50:53]
	v_mfma_f32_16x16x32_bf16 v[38:41], v[174:177], v[198:201], v[38:41]
	v_mfma_f32_16x16x32_bf16 v[18:21], v[182:185], v[206:209], v[18:21]
	v_mfma_f32_16x16x32_bf16 v[6:9], v[174:177], v[214:217], v[6:9]
	v_mfma_f32_16x16x32_bf16 v[54:57], v[178:181], v[194:197], v[54:57]
	v_mfma_f32_16x16x32_bf16 v[34:37], v[186:189], v[202:205], v[34:37]
	v_mfma_f32_16x16x32_bf16 v[22:25], v[178:181], v[210:213], v[22:25]
	v_mfma_f32_16x16x32_bf16 v[2:5], v[186:189], v[218:221], v[2:5]
	v_mfma_f32_16x16x32_bf16 v[50:53], v[186:189], v[194:197], v[50:53]
	v_mfma_f32_16x16x32_bf16 v[38:41], v[178:181], v[202:205], v[38:41]
	v_mfma_f32_16x16x32_bf16 v[18:21], v[186:189], v[210:213], v[18:21]
	v_mfma_f32_16x16x32_bf16 v[6:9], v[178:181], v[218:221], v[6:9]
	s_barrier
	s_setprio 0
	s_add_i32 s84, s84, 2
	s_add_u32 s46, s46, 0x100
	s_addc_u32 s47, s47, 0
	s_add_u32 s82, s82, 0x100
	s_addc_u32 s83, s83, 0
	s_cmp_gt_u32 s84, 41
	s_cbranch_scc0 .LBB0_221
	s_and_b64 vcc, exec, s[42:43]
	s_cbranch_vccz .LBB0_224
	s_barrier

; #define PG8_STAGE(bufoff, gbase, voff) do { _Pragma("unroll") for (int _i = 0; _i < 2; ++_i) \
;         __builtin_amdgcn_global_load_lds((const unsigned*)((const char*)(gbase) + (voff)[_i]), (LAS unsigned*)(lds + (bufoff) + ldsw + _i * 8192), 16, 0, 0); } while (0)
; #define PG8_LDA(dst, b, h) do { _Pragma("unroll") for (int m = 0; m < 4; ++m) _Pragma("unroll") for (int k = 0; k < 2; ++k) dst[m][k] = *(const LAS bf16x8*)(lds + PG8_SA(b, h) + aoff + m * 2048 + k * 1024); } while (0)
; #define PG8_LDB(dst, b, h) do { _Pragma("unroll") for (int n = 0; n < 2; ++n) _Pragma("unroll") for (int k = 0; k < 2; ++k) dst[n][k] = *(const LAS bf16x8*)(lds + PG8_SB(b, h) + boff + n * 2048 + k * 1024); } while (0)
; #define PG8_MMA(ai, bj, At, Bt) do { __builtin_amdgcn_s_setprio(1); _Pragma("unroll") for (int m = 0; m < 4; ++m) _Pragma("unroll") for (int n = 0; n < 2; ++n) _Pragma("unroll") for (int k = 0; k < 2; ++k) \
;         acc[ai][bj][m][n] = __builtin_amdgcn_mfma_f32_16x16x32_bf16(Bt[n][k], At[m][k], acc[ai][bj][m][n], 0, 0, 0); __builtin_amdgcn_s_setprio(0); } while (0)
; #define PG8_WAIT_V(n) asm volatile("s_waitcnt vmcnt(" #n ")" ::: "memory")
; #define PG8_WAIT_L(n) asm volatile("s_waitcnt lgkmcnt(" #n ")" ::: "memory")
; #define PG8_BAR __builtin_amdgcn_s_barrier()
; template <class Epi>
; __device__ __forceinline__ void gemm_phase(LAS unsigned char* lds, const Gemm g, const StaticOrder& S, const Epi& E) {
;     ...
;             const bool last = (t == nt - 2);
;             const char* a1 = cA + (size_t)(t + 1) * kstep;
;             const char* a2 = last ? nA : cA + (size_t)(t + 2) * kstep; const char* b2 = last ? nB : cB + (size_t)(t + 2) * kstep;
;             const char* a3 = a2 + kstep; const char* b3 = b2 + kstep;
;             if constexpr (Epi::MIDK > 0) { if (t == Epi::MIDK) E.mid(acc, cur, wr, wc, fr, fq); }
;             PG8_LDB(B0, 0, 0); PG8_LDB(B1, 0, 1); PG8_SCHED; PG8_LDA(At, 0, 0); PG8_STAGE(PG8_SA(1, 1), a1 + hstep, voffA);
;             PG8_WAIT_V(8); PG8_WAIT_L(0); PG8_BAR; PG8_MMA(0, 0, At, B0); PG8_MMA(0, 1, At, B1); PG8_BAR; PG8_SCHED;
;             PG8_LDA(At, 0, 1); PG8_STAGE(PG8_SB(0, 0), b2, voffB); PG8_STAGE(PG8_SB(0, 1), b2 + hstep, voffB); PG8_STAGE(PG8_SA(0, 0), a2, voffA);
;             PG8_WAIT_V(8); PG8_WAIT_L(0); PG8_BAR; PG8_MMA(1, 0, At, B0); PG8_MMA(1, 1, At, B1); PG8_BAR; PG8_SCHED;
.LBB0_322:
	ds_read_b128 v[130:133], v191
	ds_read_b128 v[134:137], v191 offset:1024
	ds_read_b128 v[138:141], v191 offset:2048
	ds_read_b128 v[142:145], v191 offset:3072
	ds_read_b128 v[166:169], v193
	ds_read_b128 v[172:175], v193 offset:1024
	ds_read_b128 v[176:179], v193 offset:2048
	ds_read_b128 v[180:183], v193 offset:3072
	s_add_u32 s76, s88, 0xfffc0080
	s_addc_u32 s77, s89, -1
	s_cmp_eq_u32 vcc_hi, 12
	s_cselect_b32 s93, s1, s77
	s_cselect_b32 s92, s7, s76
	s_cselect_b32 s91, s9, vcc_lo
	s_cselect_b32 s90, s46, s81
	s_add_i32 m0, s96, 0xc000
	ds_read_b128 v[200:203], v194
	ds_read_b128 v[204:207], v194 offset:1024
	ds_read_b128 v[208:211], v194 offset:2048
	ds_read_b128 v[212:215], v194 offset:3072
	ds_read_b128 v[216:219], v194 offset:4096
	ds_read_b128 v[220:223], v194 offset:5120
	ds_read_b128 v[224:227], v194 offset:6144
	ds_read_b128 v[228:231], v194 offset:7168
	global_load_lds_dwordx4 v158, s[88:89]
	s_add_i32 m0, s96, 0xe000
	s_nop 0
	global_load_lds_dwordx4 v160, s[88:89]
	s_waitcnt vmcnt(8)
	s_waitcnt lgkmcnt(0)
	s_setprio 1
	s_barrier
	v_mfma_f32_16x16x32_bf16 v[126:129], v[130:133], v[200:203], v[126:129]
	v_mfma_f32_16x16x32_bf16 v[106:109], v[138:141], v[208:211], v[106:109]
	v_mfma_f32_16x16x32_bf16 v[94:97], v[130:133], v[216:219], v[94:97]
	v_mfma_f32_16x16x32_bf16 v[74:77], v[138:141], v[224:227], v[74:77]
	v_mfma_f32_16x16x32_bf16 v[122:125], v[138:141], v[200:203], v[122:125]
	v_mfma_f32_16x16x32_bf16 v[110:113], v[130:133], v[208:211], v[110:113]
	v_mfma_f32_16x16x32_bf16 v[90:93], v[138:141], v[216:219], v[90:93]
	v_mfma_f32_16x16x32_bf16 v[78:81], v[130:133], v[224:227], v[78:81]
	v_mfma_f32_16x16x32_bf16 v[126:129], v[134:137], v[204:207], v[126:129]
	v_mfma_f32_16x16x32_bf16 v[106:109], v[142:145], v[212:215], v[106:109]
	v_mfma_f32_16x16x32_bf16 v[94:97], v[134:137], v[220:223], v[94:97]
	v_mfma_f32_16x16x32_bf16 v[74:77], v[142:145], v[228:231], v[74:77]
	v_mfma_f32_16x16x32_bf16 v[122:125], v[142:145], v[204:207], v[122:125]
	v_mfma_f32_16x16x32_bf16 v[110:113], v[134:137], v[212:215], v[110:113]
	v_mfma_f32_16x16x32_bf16 v[90:93], v[142:145], v[220:223], v[90:93]
	v_mfma_f32_16x16x32_bf16 v[78:81], v[134:137], v[228:231], v[78:81]
	v_mfma_f32_16x16x32_bf16 v[118:121], v[166:169], v[200:203], v[118:121]
	v_mfma_f32_16x16x32_bf16 v[98:101], v[176:179], v[208:211], v[98:101]
	v_mfma_f32_16x16x32_bf16 v[86:89], v[166:169], v[216:219], v[86:89]
	v_mfma_f32_16x16x32_bf16 v[66:69], v[176:179], v[224:227], v[66:69]
	v_mfma_f32_16x16x32_bf16 v[114:117], v[176:179], v[200:203], v[114:117]
	v_mfma_f32_16x16x32_bf16 v[102:105], v[166:169], v[208:211], v[102:105]
	v_mfma_f32_16x16x32_bf16 v[82:85], v[176:179], v[216:219], v[82:85]
	v_mfma_f32_16x16x32_bf16 v[70:73], v[166:169], v[224:227], v[70:73]
	v_mfma_f32_16x16x32_bf16 v[118:121], v[172:175], v[204:207], v[118:121]
	v_mfma_f32_16x16x32_bf16 v[98:101], v[180:183], v[212:215], v[98:101]
	v_mfma_f32_16x16x32_bf16 v[86:89], v[172:175], v[220:223], v[86:89]
	v_mfma_f32_16x16x32_bf16 v[66:69], v[180:183], v[228:231], v[66:69]
	v_mfma_f32_16x16x32_bf16 v[114:117], v[180:183], v[204:207], v[114:117]
	v_mfma_f32_16x16x32_bf16 v[102:105], v[172:175], v[212:215], v[102:105]
	v_mfma_f32_16x16x32_bf16 v[82:85], v[180:183], v[220:223], v[82:85]
	v_mfma_f32_16x16x32_bf16 v[70:73], v[172:175], v[228:231], v[70:73]
	s_barrier
	s_setprio 0
	s_add_u32 s98, s90, s50
	s_addc_u32 s99, s91, s51
	s_add_u32 s100, s92, s50
	s_addc_u32 s101, s93, s51
	s_add_i32 s76, s42, s44
	s_mov_b32 m0, s76
	ds_read_b128 v[200:203], v194 offset:16384
	ds_read_b128 v[204:207], v194 offset:17408
	ds_read_b128 v[208:211], v194 offset:18432
	ds_read_b128 v[212:215], v194 offset:19456
	ds_read_b128 v[216:219], v194 offset:20480
	ds_read_b128 v[220:223], v194 offset:21504
	ds_read_b128 v[224:227], v194 offset:22528
	ds_read_b128 v[228:231], v194 offset:23552
	global_load_lds_dwordx4 v148, s[90:91]
	s_add_i32 m0, s76, 0x2000
	s_add_u32 s76, s90, 0x40000
	s_addc_u32 s77, s91, 0
	s_add_i32 s60, s43, s44
	global_load_lds_dwordx4 v152, s[90:91]
	s_mov_b32 m0, s60
	s_nop 0
	global_load_lds_dwordx4 v148, s[76:77]
	s_add_i32 m0, s60, 0x2000
	s_nop 0
	global_load_lds_dwordx4 v152, s[76:77]
	s_mov_b32 m0, s96
	s_nop 0
	global_load_lds_dwordx4 v146, s[92:93]
	s_mov_b32 m0, s97
	s_nop 0
	global_load_lds_dwordx4 v150, s[92:93]
	s_waitcnt vmcnt(8)
	s_waitcnt lgkmcnt(0)
	s_setprio 1
	s_barrier
	v_mfma_f32_16x16x32_bf16 v[62:65], v[130:133], v[200:203], v[62:65]
	v_mfma_f32_16x16x32_bf16 v[42:45], v[138:141], v[208:211], v[42:45]
	v_mfma_f32_16x16x32_bf16 v[30:33], v[130:133], v[216:219], v[30:33]
	v_mfma_f32_16x16x32_bf16 v[10:13], v[138:141], v[224:227], v[10:13]
	v_mfma_f32_16x16x32_bf16 v[58:61], v[138:141], v[200:203], v[58:61]
	v_mfma_f32_16x16x32_bf16 v[46:49], v[130:133], v[208:211], v[46:49]
	v_mfma_f32_16x16x32_bf16 v[26:29], v[138:141], v[216:219], v[26:29]
	v_mfma_f32_16x16x32_bf16 v[14:17], v[130:133], v[224:227], v[14:17]
	v_mfma_f32_16x16x32_bf16 v[62:65], v[134:137], v[204:207], v[62:65]
	v_mfma_f32_16x16x32_bf16 v[42:45], v[142:145], v[212:215], v[42:45]
	v_mfma_f32_16x16x32_bf16 v[30:33], v[134:137], v[220:223], v[30:33]
	v_mfma_f32_16x16x32_bf16 v[10:13], v[142:145], v[228:231], v[10:13]
	v_mfma_f32_16x16x32_bf16 v[58:61], v[142:145], v[204:207], v[58:61]
	v_mfma_f32_16x16x32_bf16 v[46:49], v[134:137], v[212:215], v[46:49]
	v_mfma_f32_16x16x32_bf16 v[26:29], v[142:145], v[220:223], v[26:29]
	v_mfma_f32_16x16x32_bf16 v[14:17], v[134:137], v[228:231], v[14:17]
	v_mfma_f32_16x16x32_bf16 v[54:57], v[166:169], v[200:203], v[54:57]
	v_mfma_f32_16x16x32_bf16 v[34:37], v[176:179], v[208:211], v[34:37]
	v_mfma_f32_16x16x32_bf16 v[22:25], v[166:169], v[216:219], v[22:25]
	v_mfma_f32_16x16x32_bf16 v[2:5], v[176:179], v[224:227], v[2:5]
	v_mfma_f32_16x16x32_bf16 v[50:53], v[176:179], v[200:203], v[50:53]
	v_mfma_f32_16x16x32_bf16 v[38:41], v[166:169], v[208:211], v[38:41]
	v_mfma_f32_16x16x32_bf16 v[18:21], v[176:179], v[216:219], v[18:21]
	v_mfma_f32_16x16x32_bf16 v[6:9], v[166:169], v[224:227], v[6:9]
	v_mfma_f32_16x16x32_bf16 v[54:57], v[172:175], v[204:207], v[54:57]
	v_mfma_f32_16x16x32_bf16 v[34:37], v[180:183], v[212:215], v[34:37]
	v_mfma_f32_16x16x32_bf16 v[22:25], v[172:175], v[220:223], v[22:25]
	v_mfma_f32_16x16x32_bf16 v[2:5], v[180:183], v[228:231], v[2:5]
	v_mfma_f32_16x16x32_bf16 v[50:53], v[180:183], v[204:207], v[50:53]
	v_mfma_f32_16x16x32_bf16 v[38:41], v[172:175], v[212:215], v[38:41]
	v_mfma_f32_16x16x32_bf16 v[18:21], v[180:183], v[220:223], v[18:21]
	v_mfma_f32_16x16x32_bf16 v[6:9], v[172:175], v[228:231], v[6:9]
	s_barrier
; #define PG8_STAGE(bufoff, gbase, voff) do { _Pragma("unroll") for (int _i = 0; _i < 2; ++_i) \
;         __builtin_amdgcn_global_load_lds((const unsigned*)((const char*)(gbase) + (voff)[_i]), (LAS unsigned*)(lds + (bufoff) + ldsw + _i * 8192), 16, 0, 0); } while (0)
; #define PG8_LDA(dst, b, h) do { _Pragma("unroll") for (int m = 0; m < 4; ++m) _Pragma("unroll") for (int k = 0; k < 2; ++k) dst[m][k] = *(const LAS bf16x8*)(lds + PG8_SA(b, h) + aoff + m * 2048 + k * 1024); } while (0)
; #define PG8_LDB(dst, b, h) do { _Pragma("unroll") for (int n = 0; n < 2; ++n) _Pragma("unroll") for (int k = 0; k < 2; ++k) dst[n][k] = *(const LAS bf16x8*)(lds + PG8_SB(b, h) + boff + n * 2048 + k * 1024); } while (0)
; #define PG8_MMA(ai, bj, At, Bt) do { __builtin_amdgcn_s_setprio(1); _Pragma("unroll") for (int m = 0; m < 4; ++m) _Pragma("unroll") for (int n = 0; n < 2; ++n) _Pragma("unroll") for (int k = 0; k < 2; ++k) \
;         acc[ai][bj][m][n] = __builtin_amdgcn_mfma_f32_16x16x32_bf16(Bt[n][k], At[m][k], acc[ai][bj][m][n], 0, 0, 0); __builtin_amdgcn_s_setprio(0); } while (0)
; #define PG8_WAIT_V(n) asm volatile("s_waitcnt vmcnt(" #n ")" ::: "memory")
; #define PG8_WAIT_L(n) asm volatile("s_waitcnt lgkmcnt(" #n ")" ::: "memory")
; #define PG8_BAR __builtin_amdgcn_s_barrier()
; #define PG8_SCHED __builtin_amdgcn_sched_barrier(0)
; template <class Epi>
; __device__ __forceinline__ void gemm_phase(LAS unsigned char* lds, const Gemm g, const StaticOrder& S, const Epi& E) {
;     ...
;             PG8_LDB(B0, 1, 0); PG8_LDB(B1, 1, 1); PG8_SCHED; PG8_LDA(At, 1, 0); PG8_STAGE(PG8_SA(0, 1), a2 + hstep, voffA);
;             PG8_WAIT_V(8); PG8_WAIT_L(0); PG8_BAR; PG8_MMA(0, 0, At, B0); PG8_MMA(0, 1, At, B1); PG8_BAR; PG8_SCHED;
;             PG8_LDA(At, 1, 1); PG8_STAGE(PG8_SB(1, 0), b3, voffB); PG8_STAGE(PG8_SB(1, 1), b3 + hstep, voffB); PG8_STAGE(PG8_SA(1, 0), a3, voffA);
;             PG8_WAIT_V(8); PG8_WAIT_L(0); PG8_BAR; PG8_MMA(1, 0, At, B0); PG8_MMA(1, 1, At, B1); PG8_BAR; PG8_SCHED;
;         }
;         if (wr == 0) PG8_BAR;
	s_setprio 0
	s_add_i32 s60, 0, 0x18000
	s_add_i32 s61, 0, 0x1c000
	v_add_u32_e32 v142, s60, v187
	v_add_u32_e32 v180, s61, v187
	ds_read_b128 v[130:133], v142
	ds_read_b128 v[134:137], v142 offset:1024
	ds_read_b128 v[138:141], v142 offset:2048
	ds_read_b128 v[142:145], v142 offset:3072
	ds_read_b128 v[166:169], v180
	ds_read_b128 v[172:175], v180 offset:1024
	ds_read_b128 v[176:179], v180 offset:2048
	ds_read_b128 v[180:183], v180 offset:3072
	s_add_u32 s76, s92, 0x40000
	s_addc_u32 s77, s93, 0
	s_mov_b32 m0, s11
	ds_read_b128 v[200:203], v194 offset:32768
	ds_read_b128 v[204:207], v194 offset:33792
	ds_read_b128 v[208:211], v194 offset:34816
	ds_read_b128 v[212:215], v194 offset:35840
	ds_read_b128 v[216:219], v194 offset:36864
	ds_read_b128 v[220:223], v194 offset:37888
	ds_read_b128 v[224:227], v194 offset:38912
	ds_read_b128 v[228:231], v194 offset:39936
	global_load_lds_dwordx4 v146, s[76:77]
	s_mov_b32 m0, s94
	s_nop 0
	global_load_lds_dwordx4 v150, s[76:77]
	s_waitcnt vmcnt(8)
	s_waitcnt lgkmcnt(0)
	s_setprio 1
	s_barrier
	v_mfma_f32_16x16x32_bf16 v[126:129], v[130:133], v[200:203], v[126:129]
	v_mfma_f32_16x16x32_bf16 v[106:109], v[138:141], v[208:211], v[106:109]
	v_mfma_f32_16x16x32_bf16 v[94:97], v[130:133], v[216:219], v[94:97]
	v_mfma_f32_16x16x32_bf16 v[74:77], v[138:141], v[224:227], v[74:77]
	v_mfma_f32_16x16x32_bf16 v[122:125], v[138:141], v[200:203], v[122:125]
	v_mfma_f32_16x16x32_bf16 v[110:113], v[130:133], v[208:211], v[110:113]
	v_mfma_f32_16x16x32_bf16 v[90:93], v[138:141], v[216:219], v[90:93]
	v_mfma_f32_16x16x32_bf16 v[78:81], v[130:133], v[224:227], v[78:81]
	v_mfma_f32_16x16x32_bf16 v[126:129], v[134:137], v[204:207], v[126:129]
	v_mfma_f32_16x16x32_bf16 v[106:109], v[142:145], v[212:215], v[106:109]
	v_mfma_f32_16x16x32_bf16 v[94:97], v[134:137], v[220:223], v[94:97]
	v_mfma_f32_16x16x32_bf16 v[74:77], v[142:145], v[228:231], v[74:77]
	v_mfma_f32_16x16x32_bf16 v[122:125], v[142:145], v[204:207], v[122:125]
	v_mfma_f32_16x16x32_bf16 v[110:113], v[134:137], v[212:215], v[110:113]
	v_mfma_f32_16x16x32_bf16 v[90:93], v[142:145], v[220:223], v[90:93]
	v_mfma_f32_16x16x32_bf16 v[78:81], v[134:137], v[228:231], v[78:81]
	v_mfma_f32_16x16x32_bf16 v[118:121], v[166:169], v[200:203], v[118:121]
	v_mfma_f32_16x16x32_bf16 v[98:101], v[176:179], v[208:211], v[98:101]
	v_mfma_f32_16x16x32_bf16 v[86:89], v[166:169], v[216:219], v[86:89]
	v_mfma_f32_16x16x32_bf16 v[66:69], v[176:179], v[224:227], v[66:69]
	v_mfma_f32_16x16x32_bf16 v[114:117], v[176:179], v[200:203], v[114:117]
	v_mfma_f32_16x16x32_bf16 v[102:105], v[166:169], v[208:211], v[102:105]
	v_mfma_f32_16x16x32_bf16 v[82:85], v[176:179], v[216:219], v[82:85]
	v_mfma_f32_16x16x32_bf16 v[70:73], v[166:169], v[224:227], v[70:73]
	v_mfma_f32_16x16x32_bf16 v[118:121], v[172:175], v[204:207], v[118:121]
	v_mfma_f32_16x16x32_bf16 v[98:101], v[180:183], v[212:215], v[98:101]
	v_mfma_f32_16x16x32_bf16 v[86:89], v[172:175], v[220:223], v[86:89]
	v_mfma_f32_16x16x32_bf16 v[66:69], v[180:183], v[228:231], v[66:69]
	v_mfma_f32_16x16x32_bf16 v[114:117], v[180:183], v[204:207], v[114:117]
	v_mfma_f32_16x16x32_bf16 v[102:105], v[172:175], v[212:215], v[102:105]
	v_mfma_f32_16x16x32_bf16 v[82:85], v[180:183], v[220:223], v[82:85]
	v_mfma_f32_16x16x32_bf16 v[70:73], v[172:175], v[228:231], v[70:73]
	s_barrier
	s_setprio 0
	s_add_i32 s60, s60, s44
	s_mov_b32 m0, s60
	ds_read_b128 v[200:203], v194 offset:49152
	ds_read_b128 v[204:207], v194 offset:50176
	ds_read_b128 v[208:211], v194 offset:51200
	ds_read_b128 v[212:215], v194 offset:52224
	ds_read_b128 v[216:219], v194 offset:53248
	ds_read_b128 v[220:223], v194 offset:54272
	ds_read_b128 v[224:227], v194 offset:55296
	ds_read_b128 v[228:231], v194 offset:56320
	global_load_lds_dwordx4 v148, s[98:99]
	s_add_i32 m0, s60, 0x2000
	s_add_u32 s76, s90, 0x40080
	s_addc_u32 s77, s91, 0
	s_add_i32 s60, s61, s44
	global_load_lds_dwordx4 v152, s[98:99]
	s_mov_b32 m0, s60
	s_nop 0
	global_load_lds_dwordx4 v148, s[76:77]
	s_add_i32 m0, s60, 0x2000
	s_nop 0
	global_load_lds_dwordx4 v152, s[76:77]
	s_mov_b32 m0, s79
	s_nop 0
	global_load_lds_dwordx4 v146, s[100:101]
	s_mov_b32 m0, s33
	s_nop 0
	global_load_lds_dwordx4 v150, s[100:101]
	s_waitcnt vmcnt(8)
	s_waitcnt lgkmcnt(0)
	s_setprio 1
	s_barrier
	v_mfma_f32_16x16x32_bf16 v[62:65], v[130:133], v[200:203], v[62:65]
	v_mfma_f32_16x16x32_bf16 v[42:45], v[138:141], v[208:211], v[42:45]
	v_mfma_f32_16x16x32_bf16 v[30:33], v[130:133], v[216:219], v[30:33]
	v_mfma_f32_16x16x32_bf16 v[10:13], v[138:141], v[224:227], v[10:13]
	v_mfma_f32_16x16x32_bf16 v[58:61], v[138:141], v[200:203], v[58:61]
	v_mfma_f32_16x16x32_bf16 v[46:49], v[130:133], v[208:211], v[46:49]
	v_mfma_f32_16x16x32_bf16 v[26:29], v[138:141], v[216:219], v[26:29]
	v_mfma_f32_16x16x32_bf16 v[14:17], v[130:133], v[224:227], v[14:17]
	v_mfma_f32_16x16x32_bf16 v[62:65], v[134:137], v[204:207], v[62:65]
	v_mfma_f32_16x16x32_bf16 v[42:45], v[142:145], v[212:215], v[42:45]
	v_mfma_f32_16x16x32_bf16 v[30:33], v[134:137], v[220:223], v[30:33]
	v_mfma_f32_16x16x32_bf16 v[10:13], v[142:145], v[228:231], v[10:13]
	v_mfma_f32_16x16x32_bf16 v[58:61], v[142:145], v[204:207], v[58:61]
	v_mfma_f32_16x16x32_bf16 v[46:49], v[134:137], v[212:215], v[46:49]
	v_mfma_f32_16x16x32_bf16 v[26:29], v[142:145], v[220:223], v[26:29]
	v_mfma_f32_16x16x32_bf16 v[14:17], v[134:137], v[228:231], v[14:17]
	v_mfma_f32_16x16x32_bf16 v[54:57], v[166:169], v[200:203], v[54:57]
	v_mfma_f32_16x16x32_bf16 v[34:37], v[176:179], v[208:211], v[34:37]
	v_mfma_f32_16x16x32_bf16 v[22:25], v[166:169], v[216:219], v[22:25]
	v_mfma_f32_16x16x32_bf16 v[2:5], v[176:179], v[224:227], v[2:5]
	v_mfma_f32_16x16x32_bf16 v[50:53], v[176:179], v[200:203], v[50:53]
	v_mfma_f32_16x16x32_bf16 v[38:41], v[166:169], v[208:211], v[38:41]
	v_mfma_f32_16x16x32_bf16 v[18:21], v[176:179], v[216:219], v[18:21]
	v_mfma_f32_16x16x32_bf16 v[6:9], v[166:169], v[224:227], v[6:9]
	v_mfma_f32_16x16x32_bf16 v[54:57], v[172:175], v[204:207], v[54:57]
	v_mfma_f32_16x16x32_bf16 v[34:37], v[180:183], v[212:215], v[34:37]
	v_mfma_f32_16x16x32_bf16 v[22:25], v[172:175], v[220:223], v[22:25]
	v_mfma_f32_16x16x32_bf16 v[2:5], v[180:183], v[228:231], v[2:5]
	v_mfma_f32_16x16x32_bf16 v[50:53], v[180:183], v[204:207], v[50:53]
	v_mfma_f32_16x16x32_bf16 v[38:41], v[172:175], v[212:215], v[38:41]
	v_mfma_f32_16x16x32_bf16 v[18:21], v[180:183], v[220:223], v[18:21]
	v_mfma_f32_16x16x32_bf16 v[6:9], v[172:175], v[228:231], v[6:9]
	s_barrier
	s_setprio 0
	s_add_i32 vcc_hi, vcc_hi, 2
	s_add_u32 s88, s88, 0x100
	s_addc_u32 s89, s89, 0
	s_add_u32 s81, s81, 0x100
	s_addc_u32 vcc_lo, vcc_lo, 0
	s_cmp_gt_u32 vcc_hi, 13
	s_cbranch_scc0 .LBB0_322
	s_and_b64 vcc, exec, s[58:59]
	s_cbranch_vccz .LBB0_325
	s_barrier

; #define PG8_STAGE(bufoff, gbase, voff) do { _Pragma("unroll") for (int _i = 0; _i < 2; ++_i) \
;         __builtin_amdgcn_global_load_lds((const unsigned*)((const char*)(gbase) + (voff)[_i]), (LAS unsigned*)(lds + (bufoff) + ldsw + _i * 8192), 16, 0, 0); } while (0)
; #define PG8_LDA(dst, b, h) do { _Pragma("unroll") for (int m = 0; m < 4; ++m) _Pragma("unroll") for (int k = 0; k < 2; ++k) dst[m][k] = *(const LAS bf16x8*)(lds + PG8_SA(b, h) + aoff + m * 2048 + k * 1024); } while (0)
; #define PG8_LDB(dst, b, h) do { _Pragma("unroll") for (int n = 0; n < 2; ++n) _Pragma("unroll") for (int k = 0; k < 2; ++k) dst[n][k] = *(const LAS bf16x8*)(lds + PG8_SB(b, h) + boff + n * 2048 + k * 1024); } while (0)
; #define PG8_MMA(ai, bj, At, Bt) do { __builtin_amdgcn_s_setprio(1); _Pragma("unroll") for (int m = 0; m < 4; ++m) _Pragma("unroll") for (int n = 0; n < 2; ++n) _Pragma("unroll") for (int k = 0; k < 2; ++k) \
;         acc[ai][bj][m][n] = __builtin_amdgcn_mfma_f32_16x16x32_bf16(Bt[n][k], At[m][k], acc[ai][bj][m][n], 0, 0, 0); __builtin_amdgcn_s_setprio(0); } while (0)
; #define PG8_WAIT_V(n) asm volatile("s_waitcnt vmcnt(" #n ")" ::: "memory")
; #define PG8_WAIT_L(n) asm volatile("s_waitcnt lgkmcnt(" #n ")" ::: "memory")
; #define PG8_BAR __builtin_amdgcn_s_barrier()
; template <class Epi>
; __device__ __forceinline__ void gemm_phase(LAS unsigned char* lds, const Gemm g, const StaticOrder& S, const Epi& E) {
;     ...
;         for (int t = 0; t < nt; t += 2) {
;             const bool last = (t == nt - 2);
;             const char* a1 = cA + (size_t)(t + 1) * kstep;
;             const char* a2 = last ? nA : cA + (size_t)(t + 2) * kstep; const char* b2 = last ? nB : cB + (size_t)(t + 2) * kstep;
;             const char* a3 = a2 + kstep; const char* b3 = b2 + kstep;
;             if constexpr (Epi::MIDK > 0) { if (t == Epi::MIDK) E.mid(acc, cur, wr, wc, fr, fq); }
;             PG8_LDB(B0, 0, 0); PG8_LDB(B1, 0, 1); PG8_SCHED; PG8_LDA(At, 0, 0); PG8_STAGE(PG8_SA(1, 1), a1 + hstep, voffA);
;             PG8_WAIT_V(8); PG8_WAIT_L(0); PG8_BAR; PG8_MMA(0, 0, At, B0); PG8_MMA(0, 1, At, B1); PG8_BAR; PG8_SCHED;
;             PG8_LDA(At, 0, 1); PG8_STAGE(PG8_SB(0, 0), b2, voffB); PG8_STAGE(PG8_SB(0, 1), b2 + hstep, voffB); PG8_STAGE(PG8_SA(0, 0), a2, voffA);
;             PG8_WAIT_V(8); PG8_WAIT_L(0); PG8_BAR; PG8_MMA(1, 0, At, B0); PG8_MMA(1, 1, At, B1); PG8_BAR; PG8_SCHED;
.LBB0_619:
	ds_read_b128 v[154:157], v174
	ds_read_b128 v[158:161], v174 offset:1024
	ds_read_b128 v[162:165], v174 offset:2048
	ds_read_b128 v[166:169], v174 offset:3072
	ds_read_b128 v[182:185], v175
	ds_read_b128 v[186:189], v175 offset:1024
	ds_read_b128 v[190:193], v175 offset:2048
	ds_read_b128 v[194:197], v175 offset:3072
	s_add_u32 s46, s44, 0xfffc0080
	s_addc_u32 s47, s45, -1
	s_cmp_eq_u32 s69, 12
	s_cselect_b32 s49, s64, s47
	s_cselect_b32 s48, s65, s46
	s_cselect_b32 s47, s25, s68
	s_cselect_b32 s46, s66, s67
	s_add_i32 m0, s43, 0xc000
	ds_read_b128 v[198:201], v176
	ds_read_b128 v[202:205], v176 offset:1024
	ds_read_b128 v[206:209], v176 offset:2048
	ds_read_b128 v[210:213], v176 offset:3072
	ds_read_b128 v[214:217], v176 offset:4096
	ds_read_b128 v[218:221], v176 offset:5120
	ds_read_b128 v[222:225], v176 offset:6144
	ds_read_b128 v[226:229], v176 offset:7168
	global_load_lds_dwordx4 v144, s[44:45]
	s_add_i32 m0, s43, 0xe000
	s_nop 0
	global_load_lds_dwordx4 v146, s[44:45]
	s_waitcnt vmcnt(8)
	s_waitcnt lgkmcnt(0)
	s_setprio 1
	s_barrier
	v_mfma_f32_16x16x32_bf16 v[126:129], v[154:157], v[198:201], v[126:129]
	v_mfma_f32_16x16x32_bf16 v[106:109], v[162:165], v[206:209], v[106:109]
	v_mfma_f32_16x16x32_bf16 v[94:97], v[154:157], v[214:217], v[94:97]
	v_mfma_f32_16x16x32_bf16 v[74:77], v[162:165], v[222:225], v[74:77]
	v_mfma_f32_16x16x32_bf16 v[122:125], v[162:165], v[198:201], v[122:125]
	v_mfma_f32_16x16x32_bf16 v[110:113], v[154:157], v[206:209], v[110:113]
	v_mfma_f32_16x16x32_bf16 v[90:93], v[162:165], v[214:217], v[90:93]
	v_mfma_f32_16x16x32_bf16 v[78:81], v[154:157], v[222:225], v[78:81]
	v_mfma_f32_16x16x32_bf16 v[126:129], v[158:161], v[202:205], v[126:129]
	v_mfma_f32_16x16x32_bf16 v[106:109], v[166:169], v[210:213], v[106:109]
	v_mfma_f32_16x16x32_bf16 v[94:97], v[158:161], v[218:221], v[94:97]
	v_mfma_f32_16x16x32_bf16 v[74:77], v[166:169], v[226:229], v[74:77]
	v_mfma_f32_16x16x32_bf16 v[122:125], v[166:169], v[202:205], v[122:125]
	v_mfma_f32_16x16x32_bf16 v[110:113], v[158:161], v[210:213], v[110:113]
	v_mfma_f32_16x16x32_bf16 v[90:93], v[166:169], v[218:221], v[90:93]
	v_mfma_f32_16x16x32_bf16 v[78:81], v[158:161], v[226:229], v[78:81]
	v_mfma_f32_16x16x32_bf16 v[118:121], v[182:185], v[198:201], v[118:121]
	v_mfma_f32_16x16x32_bf16 v[98:101], v[190:193], v[206:209], v[98:101]
	v_mfma_f32_16x16x32_bf16 v[86:89], v[182:185], v[214:217], v[86:89]
	v_mfma_f32_16x16x32_bf16 v[66:69], v[190:193], v[222:225], v[66:69]
	v_mfma_f32_16x16x32_bf16 v[114:117], v[190:193], v[198:201], v[114:117]
	v_mfma_f32_16x16x32_bf16 v[102:105], v[182:185], v[206:209], v[102:105]
	v_mfma_f32_16x16x32_bf16 v[82:85], v[190:193], v[214:217], v[82:85]
	v_mfma_f32_16x16x32_bf16 v[70:73], v[182:185], v[222:225], v[70:73]
	v_mfma_f32_16x16x32_bf16 v[118:121], v[186:189], v[202:205], v[118:121]
	v_mfma_f32_16x16x32_bf16 v[98:101], v[194:197], v[210:213], v[98:101]
	v_mfma_f32_16x16x32_bf16 v[86:89], v[186:189], v[218:221], v[86:89]
	v_mfma_f32_16x16x32_bf16 v[66:69], v[194:197], v[226:229], v[66:69]
	v_mfma_f32_16x16x32_bf16 v[114:117], v[194:197], v[202:205], v[114:117]
	v_mfma_f32_16x16x32_bf16 v[102:105], v[186:189], v[210:213], v[102:105]
	v_mfma_f32_16x16x32_bf16 v[82:85], v[194:197], v[218:221], v[82:85]
	v_mfma_f32_16x16x32_bf16 v[70:73], v[186:189], v[226:229], v[70:73]
	s_barrier
	s_setprio 0
	s_add_u32 s98, s46, s8
	s_addc_u32 s99, s47, s9
	s_add_u32 s100, s48, s8
	s_addc_u32 s101, s49, s9
	s_add_i32 s76, s60, s6
	s_mov_b32 m0, s76
	ds_read_b128 v[198:201], v176 offset:16384
	ds_read_b128 v[202:205], v176 offset:17408
	ds_read_b128 v[206:209], v176 offset:18432
	ds_read_b128 v[210:213], v176 offset:19456
	ds_read_b128 v[214:217], v176 offset:20480
	ds_read_b128 v[218:221], v176 offset:21504
	ds_read_b128 v[222:225], v176 offset:22528
	ds_read_b128 v[226:229], v176 offset:23552
	global_load_lds_dwordx4 v132, s[46:47]
	s_add_i32 m0, s76, 0x2000
	s_add_u32 s76, s46, 0x40000
	s_addc_u32 s77, s47, 0
	s_add_i32 s78, s61, s6
	global_load_lds_dwordx4 v136, s[46:47]
	s_mov_b32 m0, s78
	s_nop 0
	global_load_lds_dwordx4 v132, s[76:77]
	s_add_i32 m0, s78, 0x2000
	s_nop 0
	global_load_lds_dwordx4 v136, s[76:77]
	s_mov_b32 m0, s43
	s_nop 0
	global_load_lds_dwordx4 v130, s[48:49]
	s_mov_b32 m0, s51
	s_nop 0
	global_load_lds_dwordx4 v134, s[48:49]
	s_waitcnt vmcnt(8)
	s_waitcnt lgkmcnt(0)
	s_setprio 1
	s_barrier
	v_mfma_f32_16x16x32_bf16 v[62:65], v[154:157], v[198:201], v[62:65]
	v_mfma_f32_16x16x32_bf16 v[42:45], v[162:165], v[206:209], v[42:45]
	v_mfma_f32_16x16x32_bf16 v[30:33], v[154:157], v[214:217], v[30:33]
	v_mfma_f32_16x16x32_bf16 v[10:13], v[162:165], v[222:225], v[10:13]
	v_mfma_f32_16x16x32_bf16 v[58:61], v[162:165], v[198:201], v[58:61]
	v_mfma_f32_16x16x32_bf16 v[46:49], v[154:157], v[206:209], v[46:49]
	v_mfma_f32_16x16x32_bf16 v[26:29], v[162:165], v[214:217], v[26:29]
	v_mfma_f32_16x16x32_bf16 v[14:17], v[154:157], v[222:225], v[14:17]
	v_mfma_f32_16x16x32_bf16 v[62:65], v[158:161], v[202:205], v[62:65]
	v_mfma_f32_16x16x32_bf16 v[42:45], v[166:169], v[210:213], v[42:45]
	v_mfma_f32_16x16x32_bf16 v[30:33], v[158:161], v[218:221], v[30:33]
	v_mfma_f32_16x16x32_bf16 v[10:13], v[166:169], v[226:229], v[10:13]
	v_mfma_f32_16x16x32_bf16 v[58:61], v[166:169], v[202:205], v[58:61]
	v_mfma_f32_16x16x32_bf16 v[46:49], v[158:161], v[210:213], v[46:49]
	v_mfma_f32_16x16x32_bf16 v[26:29], v[166:169], v[218:221], v[26:29]
	v_mfma_f32_16x16x32_bf16 v[14:17], v[158:161], v[226:229], v[14:17]
	v_mfma_f32_16x16x32_bf16 v[54:57], v[182:185], v[198:201], v[54:57]
	v_mfma_f32_16x16x32_bf16 v[34:37], v[190:193], v[206:209], v[34:37]
	v_mfma_f32_16x16x32_bf16 v[22:25], v[182:185], v[214:217], v[22:25]
	v_mfma_f32_16x16x32_bf16 v[2:5], v[190:193], v[222:225], v[2:5]
	v_mfma_f32_16x16x32_bf16 v[50:53], v[190:193], v[198:201], v[50:53]
	v_mfma_f32_16x16x32_bf16 v[38:41], v[182:185], v[206:209], v[38:41]
	v_mfma_f32_16x16x32_bf16 v[18:21], v[190:193], v[214:217], v[18:21]
	v_mfma_f32_16x16x32_bf16 v[6:9], v[182:185], v[222:225], v[6:9]
	v_mfma_f32_16x16x32_bf16 v[54:57], v[186:189], v[202:205], v[54:57]
	v_mfma_f32_16x16x32_bf16 v[34:37], v[194:197], v[210:213], v[34:37]
	v_mfma_f32_16x16x32_bf16 v[22:25], v[186:189], v[218:221], v[22:25]
	v_mfma_f32_16x16x32_bf16 v[2:5], v[194:197], v[226:229], v[2:5]
	v_mfma_f32_16x16x32_bf16 v[50:53], v[194:197], v[202:205], v[50:53]
	v_mfma_f32_16x16x32_bf16 v[38:41], v[186:189], v[210:213], v[38:41]
	v_mfma_f32_16x16x32_bf16 v[18:21], v[194:197], v[218:221], v[18:21]
	v_mfma_f32_16x16x32_bf16 v[6:9], v[186:189], v[226:229], v[6:9]
	s_barrier
; #define PG8_STAGE(bufoff, gbase, voff) do { _Pragma("unroll") for (int _i = 0; _i < 2; ++_i) \
;         __builtin_amdgcn_global_load_lds((const unsigned*)((const char*)(gbase) + (voff)[_i]), (LAS unsigned*)(lds + (bufoff) + ldsw + _i * 8192), 16, 0, 0); } while (0)
; #define PG8_LDA(dst, b, h) do { _Pragma("unroll") for (int m = 0; m < 4; ++m) _Pragma("unroll") for (int k = 0; k < 2; ++k) dst[m][k] = *(const LAS bf16x8*)(lds + PG8_SA(b, h) + aoff + m * 2048 + k * 1024); } while (0)
; #define PG8_LDB(dst, b, h) do { _Pragma("unroll") for (int n = 0; n < 2; ++n) _Pragma("unroll") for (int k = 0; k < 2; ++k) dst[n][k] = *(const LAS bf16x8*)(lds + PG8_SB(b, h) + boff + n * 2048 + k * 1024); } while (0)
; #define PG8_MMA(ai, bj, At, Bt) do { __builtin_amdgcn_s_setprio(1); _Pragma("unroll") for (int m = 0; m < 4; ++m) _Pragma("unroll") for (int n = 0; n < 2; ++n) _Pragma("unroll") for (int k = 0; k < 2; ++k) \
;         acc[ai][bj][m][n] = __builtin_amdgcn_mfma_f32_16x16x32_bf16(Bt[n][k], At[m][k], acc[ai][bj][m][n], 0, 0, 0); __builtin_amdgcn_s_setprio(0); } while (0)
; #define PG8_WAIT_V(n) asm volatile("s_waitcnt vmcnt(" #n ")" ::: "memory")
; #define PG8_WAIT_L(n) asm volatile("s_waitcnt lgkmcnt(" #n ")" ::: "memory")
; #define PG8_BAR __builtin_amdgcn_s_barrier()
; #define PG8_SCHED __builtin_amdgcn_sched_barrier(0)
; template <class Epi>
; __device__ __forceinline__ void gemm_phase(LAS unsigned char* lds, const Gemm g, const StaticOrder& S, const Epi& E) {
;     ...
;             PG8_LDB(B0, 1, 0); PG8_LDB(B1, 1, 1); PG8_SCHED; PG8_LDA(At, 1, 0); PG8_STAGE(PG8_SA(0, 1), a2 + hstep, voffA);
;             PG8_WAIT_V(8); PG8_WAIT_L(0); PG8_BAR; PG8_MMA(0, 0, At, B0); PG8_MMA(0, 1, At, B1); PG8_BAR; PG8_SCHED;
;             PG8_LDA(At, 1, 1); PG8_STAGE(PG8_SB(1, 0), b3, voffB); PG8_STAGE(PG8_SB(1, 1), b3 + hstep, voffB); PG8_STAGE(PG8_SA(1, 0), a3, voffA);
;             PG8_WAIT_V(8); PG8_WAIT_L(0); PG8_BAR; PG8_MMA(1, 0, At, B0); PG8_MMA(1, 1, At, B1); PG8_BAR; PG8_SCHED;
;         }
;         if (wr == 0) PG8_BAR;
	s_setprio 0
	s_add_i32 s76, 0, 0x18000
	v_add_u32_e32 v138, s76, v172
	s_add_i32 s77, 0, 0x1c000
	ds_read_b128 v[154:157], v138
	ds_read_b128 v[158:161], v138 offset:1024
	ds_read_b128 v[162:165], v138 offset:2048
	ds_read_b128 v[166:169], v138 offset:3072
	v_add_u32_e32 v138, s77, v172
	ds_read_b128 v[182:185], v138
	ds_read_b128 v[186:189], v138 offset:1024
	ds_read_b128 v[190:193], v138 offset:2048
	ds_read_b128 v[194:197], v138 offset:3072
	s_add_u32 s48, s48, 0x40000
	s_addc_u32 s49, s49, 0
	s_mov_b32 m0, s52
	ds_read_b128 v[198:201], v176 offset:32768
	ds_read_b128 v[202:205], v176 offset:33792
	ds_read_b128 v[206:209], v176 offset:34816
	ds_read_b128 v[210:213], v176 offset:35840
	ds_read_b128 v[214:217], v176 offset:36864
	ds_read_b128 v[218:221], v176 offset:37888
	ds_read_b128 v[222:225], v176 offset:38912
	ds_read_b128 v[226:229], v176 offset:39936
	global_load_lds_dwordx4 v130, s[48:49]
	s_mov_b32 m0, s53
	s_nop 0
	global_load_lds_dwordx4 v134, s[48:49]
	s_waitcnt vmcnt(8)
	s_waitcnt lgkmcnt(0)
	s_setprio 1
	s_barrier
	v_mfma_f32_16x16x32_bf16 v[126:129], v[154:157], v[198:201], v[126:129]
	v_mfma_f32_16x16x32_bf16 v[106:109], v[162:165], v[206:209], v[106:109]
	v_mfma_f32_16x16x32_bf16 v[94:97], v[154:157], v[214:217], v[94:97]
	v_mfma_f32_16x16x32_bf16 v[74:77], v[162:165], v[222:225], v[74:77]
	v_mfma_f32_16x16x32_bf16 v[122:125], v[162:165], v[198:201], v[122:125]
	v_mfma_f32_16x16x32_bf16 v[110:113], v[154:157], v[206:209], v[110:113]
	v_mfma_f32_16x16x32_bf16 v[90:93], v[162:165], v[214:217], v[90:93]
	v_mfma_f32_16x16x32_bf16 v[78:81], v[154:157], v[222:225], v[78:81]
	v_mfma_f32_16x16x32_bf16 v[126:129], v[158:161], v[202:205], v[126:129]
	v_mfma_f32_16x16x32_bf16 v[106:109], v[166:169], v[210:213], v[106:109]
	v_mfma_f32_16x16x32_bf16 v[94:97], v[158:161], v[218:221], v[94:97]
	v_mfma_f32_16x16x32_bf16 v[74:77], v[166:169], v[226:229], v[74:77]
	v_mfma_f32_16x16x32_bf16 v[122:125], v[166:169], v[202:205], v[122:125]
	v_mfma_f32_16x16x32_bf16 v[110:113], v[158:161], v[210:213], v[110:113]
	v_mfma_f32_16x16x32_bf16 v[90:93], v[166:169], v[218:221], v[90:93]
	v_mfma_f32_16x16x32_bf16 v[78:81], v[158:161], v[226:229], v[78:81]
	v_mfma_f32_16x16x32_bf16 v[118:121], v[182:185], v[198:201], v[118:121]
	v_mfma_f32_16x16x32_bf16 v[98:101], v[190:193], v[206:209], v[98:101]
	v_mfma_f32_16x16x32_bf16 v[86:89], v[182:185], v[214:217], v[86:89]
	v_mfma_f32_16x16x32_bf16 v[66:69], v[190:193], v[222:225], v[66:69]
	v_mfma_f32_16x16x32_bf16 v[114:117], v[190:193], v[198:201], v[114:117]
	v_mfma_f32_16x16x32_bf16 v[102:105], v[182:185], v[206:209], v[102:105]
	v_mfma_f32_16x16x32_bf16 v[82:85], v[190:193], v[214:217], v[82:85]
	v_mfma_f32_16x16x32_bf16 v[70:73], v[182:185], v[222:225], v[70:73]
	v_mfma_f32_16x16x32_bf16 v[118:121], v[186:189], v[202:205], v[118:121]
	v_mfma_f32_16x16x32_bf16 v[98:101], v[194:197], v[210:213], v[98:101]
	v_mfma_f32_16x16x32_bf16 v[86:89], v[186:189], v[218:221], v[86:89]
	v_mfma_f32_16x16x32_bf16 v[66:69], v[194:197], v[226:229], v[66:69]
	v_mfma_f32_16x16x32_bf16 v[114:117], v[194:197], v[202:205], v[114:117]
	v_mfma_f32_16x16x32_bf16 v[102:105], v[186:189], v[210:213], v[102:105]
	v_mfma_f32_16x16x32_bf16 v[82:85], v[194:197], v[218:221], v[82:85]
	v_mfma_f32_16x16x32_bf16 v[70:73], v[186:189], v[226:229], v[70:73]
	s_barrier
	s_setprio 0
	s_add_i32 s48, s76, s6
	s_mov_b32 m0, s48
	ds_read_b128 v[198:201], v176 offset:49152
	ds_read_b128 v[202:205], v176 offset:50176
	ds_read_b128 v[206:209], v176 offset:51200
	ds_read_b128 v[210:213], v176 offset:52224
	ds_read_b128 v[214:217], v176 offset:53248
	ds_read_b128 v[218:221], v176 offset:54272
	ds_read_b128 v[222:225], v176 offset:55296
	ds_read_b128 v[226:229], v176 offset:56320
	global_load_lds_dwordx4 v132, s[98:99]
	s_add_i32 m0, s48, 0x2000
	s_add_u32 s46, s46, 0x40080
	s_addc_u32 s47, s47, 0
	s_add_i32 s48, s77, s6
	global_load_lds_dwordx4 v136, s[98:99]
	s_mov_b32 m0, s48
	s_nop 0
	global_load_lds_dwordx4 v132, s[46:47]
	s_add_i32 m0, s48, 0x2000
	s_nop 0
	global_load_lds_dwordx4 v136, s[46:47]
	s_mov_b32 m0, s56
	s_nop 0
	global_load_lds_dwordx4 v130, s[100:101]
	s_mov_b32 m0, s57
	s_nop 0
	global_load_lds_dwordx4 v134, s[100:101]
	s_waitcnt vmcnt(8)
	s_waitcnt lgkmcnt(0)
	s_setprio 1
	s_barrier
	v_mfma_f32_16x16x32_bf16 v[62:65], v[154:157], v[198:201], v[62:65]
	v_mfma_f32_16x16x32_bf16 v[42:45], v[162:165], v[206:209], v[42:45]
	v_mfma_f32_16x16x32_bf16 v[30:33], v[154:157], v[214:217], v[30:33]
	v_mfma_f32_16x16x32_bf16 v[10:13], v[162:165], v[222:225], v[10:13]
	v_mfma_f32_16x16x32_bf16 v[58:61], v[162:165], v[198:201], v[58:61]
	v_mfma_f32_16x16x32_bf16 v[46:49], v[154:157], v[206:209], v[46:49]
	v_mfma_f32_16x16x32_bf16 v[26:29], v[162:165], v[214:217], v[26:29]
	v_mfma_f32_16x16x32_bf16 v[14:17], v[154:157], v[222:225], v[14:17]
	v_mfma_f32_16x16x32_bf16 v[62:65], v[158:161], v[202:205], v[62:65]
	v_mfma_f32_16x16x32_bf16 v[42:45], v[166:169], v[210:213], v[42:45]
	v_mfma_f32_16x16x32_bf16 v[30:33], v[158:161], v[218:221], v[30:33]
	v_mfma_f32_16x16x32_bf16 v[10:13], v[166:169], v[226:229], v[10:13]
	v_mfma_f32_16x16x32_bf16 v[58:61], v[166:169], v[202:205], v[58:61]
	v_mfma_f32_16x16x32_bf16 v[46:49], v[158:161], v[210:213], v[46:49]
	v_mfma_f32_16x16x32_bf16 v[26:29], v[166:169], v[218:221], v[26:29]
	v_mfma_f32_16x16x32_bf16 v[14:17], v[158:161], v[226:229], v[14:17]
	v_mfma_f32_16x16x32_bf16 v[54:57], v[182:185], v[198:201], v[54:57]
	v_mfma_f32_16x16x32_bf16 v[34:37], v[190:193], v[206:209], v[34:37]
	v_mfma_f32_16x16x32_bf16 v[22:25], v[182:185], v[214:217], v[22:25]
	v_mfma_f32_16x16x32_bf16 v[2:5], v[190:193], v[222:225], v[2:5]
	v_mfma_f32_16x16x32_bf16 v[50:53], v[190:193], v[198:201], v[50:53]
	v_mfma_f32_16x16x32_bf16 v[38:41], v[182:185], v[206:209], v[38:41]
	v_mfma_f32_16x16x32_bf16 v[18:21], v[190:193], v[214:217], v[18:21]
	v_mfma_f32_16x16x32_bf16 v[6:9], v[182:185], v[222:225], v[6:9]
	v_mfma_f32_16x16x32_bf16 v[54:57], v[186:189], v[202:205], v[54:57]
	v_mfma_f32_16x16x32_bf16 v[34:37], v[194:197], v[210:213], v[34:37]
	v_mfma_f32_16x16x32_bf16 v[22:25], v[186:189], v[218:221], v[22:25]
	v_mfma_f32_16x16x32_bf16 v[2:5], v[194:197], v[226:229], v[2:5]
	v_mfma_f32_16x16x32_bf16 v[50:53], v[194:197], v[202:205], v[50:53]
	v_mfma_f32_16x16x32_bf16 v[38:41], v[186:189], v[210:213], v[38:41]
	v_mfma_f32_16x16x32_bf16 v[18:21], v[194:197], v[218:221], v[18:21]
	v_mfma_f32_16x16x32_bf16 v[6:9], v[186:189], v[226:229], v[6:9]
	s_barrier
	s_setprio 0
	s_add_i32 s69, s69, 2
	s_add_u32 s44, s44, 0x100
	s_addc_u32 s45, s45, 0
	s_add_u32 s67, s67, 0x100
	s_addc_u32 s68, s68, 0
	s_cmp_gt_u32 s69, 13
	s_cbranch_scc0 .LBB0_619
	s_and_b64 vcc, exec, s[18:19]
	s_cbranch_vccz .LBB0_622
	s_barrier

; #define PG8_STAGE(bufoff, gbase, voff) do { _Pragma("unroll") for (int _i = 0; _i < 2; ++_i) \
;         __builtin_amdgcn_global_load_lds((const unsigned*)((const char*)(gbase) + (voff)[_i]), (LAS unsigned*)(lds + (bufoff) + ldsw + _i * 8192), 16, 0, 0); } while (0)
; #define PG8_LDA(dst, b, h) do { _Pragma("unroll") for (int m = 0; m < 4; ++m) _Pragma("unroll") for (int k = 0; k < 2; ++k) dst[m][k] = *(const LAS bf16x8*)(lds + PG8_SA(b, h) + aoff + m * 2048 + k * 1024); } while (0)
; #define PG8_LDB(dst, b, h) do { _Pragma("unroll") for (int n = 0; n < 2; ++n) _Pragma("unroll") for (int k = 0; k < 2; ++k) dst[n][k] = *(const LAS bf16x8*)(lds + PG8_SB(b, h) + boff + n * 2048 + k * 1024); } while (0)
; #define PG8_MMA(ai, bj, At, Bt) do { __builtin_amdgcn_s_setprio(1); _Pragma("unroll") for (int m = 0; m < 4; ++m) _Pragma("unroll") for (int n = 0; n < 2; ++n) _Pragma("unroll") for (int k = 0; k < 2; ++k) \
;         acc[ai][bj][m][n] = __builtin_amdgcn_mfma_f32_16x16x32_bf16(Bt[n][k], At[m][k], acc[ai][bj][m][n], 0, 0, 0); __builtin_amdgcn_s_setprio(0); } while (0)
; #define PG8_WAIT_V(n) asm volatile("s_waitcnt vmcnt(" #n ")" ::: "memory")
; #define PG8_WAIT_L(n) asm volatile("s_waitcnt lgkmcnt(" #n ")" ::: "memory")
; #define PG8_BAR __builtin_amdgcn_s_barrier()
; template <class Epi>
; __device__ __forceinline__ void gemm_phase(LAS unsigned char* lds, const Gemm g, const StaticOrder& S, const Epi& E) {
;     ...
;         for (int t = 0; t < nt; t += 2) {
;             const bool last = (t == nt - 2);
;             const char* a1 = cA + (size_t)(t + 1) * kstep;
;             const char* a2 = last ? nA : cA + (size_t)(t + 2) * kstep; const char* b2 = last ? nB : cB + (size_t)(t + 2) * kstep;
;             const char* a3 = a2 + kstep; const char* b3 = b2 + kstep;
;             if constexpr (Epi::MIDK > 0) { if (t == Epi::MIDK) E.mid(acc, cur, wr, wc, fr, fq); }
;             PG8_LDB(B0, 0, 0); PG8_LDB(B1, 0, 1); PG8_SCHED; PG8_LDA(At, 0, 0); PG8_STAGE(PG8_SA(1, 1), a1 + hstep, voffA);
;             PG8_WAIT_V(8); PG8_WAIT_L(0); PG8_BAR; PG8_MMA(0, 0, At, B0); PG8_MMA(0, 1, At, B1); PG8_BAR; PG8_SCHED;
;             PG8_LDA(At, 0, 1); PG8_STAGE(PG8_SB(0, 0), b2, voffB); PG8_STAGE(PG8_SB(0, 1), b2 + hstep, voffB); PG8_STAGE(PG8_SA(0, 0), a2, voffA);
;             PG8_WAIT_V(8); PG8_WAIT_L(0); PG8_BAR; PG8_MMA(1, 0, At, B0); PG8_MMA(1, 1, At, B1); PG8_BAR; PG8_SCHED;
.LBB0_785:
	ds_read_b128 v[130:133], v162
	ds_read_b128 v[134:137], v162 offset:1024
	ds_read_b128 v[154:157], v162 offset:2048
	ds_read_b128 v[166:169], v162 offset:3072
	ds_read_b128 v[172:175], v163
	ds_read_b128 v[176:179], v163 offset:1024
	ds_read_b128 v[180:183], v163 offset:2048
	ds_read_b128 v[184:187], v163 offset:3072
	s_add_u32 s40, s38, 0xfffc0080
	s_addc_u32 s41, s39, -1
	s_cmp_eq_u32 s63, 12
	s_cselect_b32 s43, s21, s41
	s_cselect_b32 s42, s27, s40
	s_cselect_b32 s41, s19, s62
	s_cselect_b32 s40, s60, s61
	s_add_i32 m0, s45, 0xc000
	ds_read_b128 v[188:191], v164
	ds_read_b128 v[192:195], v164 offset:1024
	ds_read_b128 v[196:199], v164 offset:2048
	ds_read_b128 v[200:203], v164 offset:3072
	ds_read_b128 v[204:207], v164 offset:4096
	ds_read_b128 v[208:211], v164 offset:5120
	ds_read_b128 v[212:215], v164 offset:6144
	ds_read_b128 v[216:219], v164 offset:7168
	global_load_lds_dwordx4 v146, s[38:39]
	s_add_i32 m0, s45, 0xe000
	s_nop 0
	global_load_lds_dwordx4 v148, s[38:39]
	s_waitcnt vmcnt(8)
	s_waitcnt lgkmcnt(0)
	s_setprio 1
	s_barrier
	v_mfma_f32_16x16x32_bf16 v[126:129], v[130:133], v[188:191], v[126:129]
	v_mfma_f32_16x16x32_bf16 v[106:109], v[154:157], v[196:199], v[106:109]
	v_mfma_f32_16x16x32_bf16 v[94:97], v[130:133], v[204:207], v[94:97]
	v_mfma_f32_16x16x32_bf16 v[74:77], v[154:157], v[212:215], v[74:77]
	v_mfma_f32_16x16x32_bf16 v[122:125], v[154:157], v[188:191], v[122:125]
	v_mfma_f32_16x16x32_bf16 v[110:113], v[130:133], v[196:199], v[110:113]
	v_mfma_f32_16x16x32_bf16 v[90:93], v[154:157], v[204:207], v[90:93]
	v_mfma_f32_16x16x32_bf16 v[78:81], v[130:133], v[212:215], v[78:81]
	v_mfma_f32_16x16x32_bf16 v[126:129], v[134:137], v[192:195], v[126:129]
	v_mfma_f32_16x16x32_bf16 v[106:109], v[166:169], v[200:203], v[106:109]
	v_mfma_f32_16x16x32_bf16 v[94:97], v[134:137], v[208:211], v[94:97]
	v_mfma_f32_16x16x32_bf16 v[74:77], v[166:169], v[216:219], v[74:77]
	v_mfma_f32_16x16x32_bf16 v[122:125], v[166:169], v[192:195], v[122:125]
	v_mfma_f32_16x16x32_bf16 v[110:113], v[134:137], v[200:203], v[110:113]
	v_mfma_f32_16x16x32_bf16 v[90:93], v[166:169], v[208:211], v[90:93]
	v_mfma_f32_16x16x32_bf16 v[78:81], v[134:137], v[216:219], v[78:81]
	v_mfma_f32_16x16x32_bf16 v[118:121], v[172:175], v[188:191], v[118:121]
	v_mfma_f32_16x16x32_bf16 v[98:101], v[180:183], v[196:199], v[98:101]
	v_mfma_f32_16x16x32_bf16 v[86:89], v[172:175], v[204:207], v[86:89]
	v_mfma_f32_16x16x32_bf16 v[66:69], v[180:183], v[212:215], v[66:69]
	v_mfma_f32_16x16x32_bf16 v[114:117], v[180:183], v[188:191], v[114:117]
	v_mfma_f32_16x16x32_bf16 v[102:105], v[172:175], v[196:199], v[102:105]
	v_mfma_f32_16x16x32_bf16 v[82:85], v[180:183], v[204:207], v[82:85]
	v_mfma_f32_16x16x32_bf16 v[70:73], v[172:175], v[212:215], v[70:73]
	v_mfma_f32_16x16x32_bf16 v[118:121], v[176:179], v[192:195], v[118:121]
	v_mfma_f32_16x16x32_bf16 v[98:101], v[184:187], v[200:203], v[98:101]
	v_mfma_f32_16x16x32_bf16 v[86:89], v[176:179], v[208:211], v[86:89]
	v_mfma_f32_16x16x32_bf16 v[66:69], v[184:187], v[216:219], v[66:69]
	v_mfma_f32_16x16x32_bf16 v[114:117], v[184:187], v[192:195], v[114:117]
	v_mfma_f32_16x16x32_bf16 v[102:105], v[176:179], v[200:203], v[102:105]
	v_mfma_f32_16x16x32_bf16 v[82:85], v[184:187], v[208:211], v[82:85]
	v_mfma_f32_16x16x32_bf16 v[70:73], v[176:179], v[216:219], v[70:73]
	s_barrier
	s_setprio 0
	s_add_u32 s98, s40, s12
	s_addc_u32 s99, s41, s13
	s_add_u32 s100, s42, s12
	s_addc_u32 s101, s43, s13
	s_add_i32 s64, s57, s44
	s_mov_b32 m0, s64
	ds_read_b128 v[188:191], v164 offset:16384
	ds_read_b128 v[192:195], v164 offset:17408
	ds_read_b128 v[196:199], v164 offset:18432
	ds_read_b128 v[200:203], v164 offset:19456
	ds_read_b128 v[204:207], v164 offset:20480
	ds_read_b128 v[208:211], v164 offset:21504
	ds_read_b128 v[212:215], v164 offset:22528
	ds_read_b128 v[216:219], v164 offset:23552
	global_load_lds_dwordx4 v140, s[40:41]
	s_add_i32 m0, s64, 0x2000
	s_add_u32 s64, s40, 0x40000
	s_addc_u32 s65, s41, 0
	s_add_i32 s66, s58, s44
	global_load_lds_dwordx4 v144, s[40:41]
	s_mov_b32 m0, s66
	s_nop 0
	global_load_lds_dwordx4 v140, s[64:65]
	s_add_i32 m0, s66, 0x2000
	s_nop 0
	global_load_lds_dwordx4 v144, s[64:65]
	s_mov_b32 m0, s45
	s_nop 0
	global_load_lds_dwordx4 v138, s[42:43]
	s_mov_b32 m0, s46
	s_nop 0
	global_load_lds_dwordx4 v142, s[42:43]
	s_waitcnt vmcnt(8)
	s_waitcnt lgkmcnt(0)
	s_setprio 1
	s_barrier
	v_mfma_f32_16x16x32_bf16 v[62:65], v[130:133], v[188:191], v[62:65]
	v_mfma_f32_16x16x32_bf16 v[42:45], v[154:157], v[196:199], v[42:45]
	v_mfma_f32_16x16x32_bf16 v[30:33], v[130:133], v[204:207], v[30:33]
	v_mfma_f32_16x16x32_bf16 v[10:13], v[154:157], v[212:215], v[10:13]
	v_mfma_f32_16x16x32_bf16 v[58:61], v[154:157], v[188:191], v[58:61]
	v_mfma_f32_16x16x32_bf16 v[46:49], v[130:133], v[196:199], v[46:49]
	v_mfma_f32_16x16x32_bf16 v[26:29], v[154:157], v[204:207], v[26:29]
	v_mfma_f32_16x16x32_bf16 v[14:17], v[130:133], v[212:215], v[14:17]
	v_mfma_f32_16x16x32_bf16 v[62:65], v[134:137], v[192:195], v[62:65]
	v_mfma_f32_16x16x32_bf16 v[42:45], v[166:169], v[200:203], v[42:45]
	v_mfma_f32_16x16x32_bf16 v[30:33], v[134:137], v[208:211], v[30:33]
	v_mfma_f32_16x16x32_bf16 v[10:13], v[166:169], v[216:219], v[10:13]
	v_mfma_f32_16x16x32_bf16 v[58:61], v[166:169], v[192:195], v[58:61]
	v_mfma_f32_16x16x32_bf16 v[46:49], v[134:137], v[200:203], v[46:49]
	v_mfma_f32_16x16x32_bf16 v[26:29], v[166:169], v[208:211], v[26:29]
	v_mfma_f32_16x16x32_bf16 v[14:17], v[134:137], v[216:219], v[14:17]
	v_mfma_f32_16x16x32_bf16 v[54:57], v[172:175], v[188:191], v[54:57]
	v_mfma_f32_16x16x32_bf16 v[34:37], v[180:183], v[196:199], v[34:37]
	v_mfma_f32_16x16x32_bf16 v[22:25], v[172:175], v[204:207], v[22:25]
	v_mfma_f32_16x16x32_bf16 v[2:5], v[180:183], v[212:215], v[2:5]
	v_mfma_f32_16x16x32_bf16 v[50:53], v[180:183], v[188:191], v[50:53]
	v_mfma_f32_16x16x32_bf16 v[38:41], v[172:175], v[196:199], v[38:41]
	v_mfma_f32_16x16x32_bf16 v[18:21], v[180:183], v[204:207], v[18:21]
	v_mfma_f32_16x16x32_bf16 v[6:9], v[172:175], v[212:215], v[6:9]
	v_mfma_f32_16x16x32_bf16 v[54:57], v[176:179], v[192:195], v[54:57]
	v_mfma_f32_16x16x32_bf16 v[34:37], v[184:187], v[200:203], v[34:37]
	v_mfma_f32_16x16x32_bf16 v[22:25], v[176:179], v[208:211], v[22:25]
	v_mfma_f32_16x16x32_bf16 v[2:5], v[184:187], v[216:219], v[2:5]
	v_mfma_f32_16x16x32_bf16 v[50:53], v[184:187], v[192:195], v[50:53]
	v_mfma_f32_16x16x32_bf16 v[38:41], v[176:179], v[200:203], v[38:41]
	v_mfma_f32_16x16x32_bf16 v[18:21], v[184:187], v[208:211], v[18:21]
	v_mfma_f32_16x16x32_bf16 v[6:9], v[176:179], v[216:219], v[6:9]
	s_barrier
; #define PG8_STAGE(bufoff, gbase, voff) do { _Pragma("unroll") for (int _i = 0; _i < 2; ++_i) \
;         __builtin_amdgcn_global_load_lds((const unsigned*)((const char*)(gbase) + (voff)[_i]), (LAS unsigned*)(lds + (bufoff) + ldsw + _i * 8192), 16, 0, 0); } while (0)
; #define PG8_LDA(dst, b, h) do { _Pragma("unroll") for (int m = 0; m < 4; ++m) _Pragma("unroll") for (int k = 0; k < 2; ++k) dst[m][k] = *(const LAS bf16x8*)(lds + PG8_SA(b, h) + aoff + m * 2048 + k * 1024); } while (0)
; #define PG8_LDB(dst, b, h) do { _Pragma("unroll") for (int n = 0; n < 2; ++n) _Pragma("unroll") for (int k = 0; k < 2; ++k) dst[n][k] = *(const LAS bf16x8*)(lds + PG8_SB(b, h) + boff + n * 2048 + k * 1024); } while (0)
; #define PG8_MMA(ai, bj, At, Bt) do { __builtin_amdgcn_s_setprio(1); _Pragma("unroll") for (int m = 0; m < 4; ++m) _Pragma("unroll") for (int n = 0; n < 2; ++n) _Pragma("unroll") for (int k = 0; k < 2; ++k) \
;         acc[ai][bj][m][n] = __builtin_amdgcn_mfma_f32_16x16x32_bf16(Bt[n][k], At[m][k], acc[ai][bj][m][n], 0, 0, 0); __builtin_amdgcn_s_setprio(0); } while (0)
; #define PG8_WAIT_V(n) asm volatile("s_waitcnt vmcnt(" #n ")" ::: "memory")
; #define PG8_WAIT_L(n) asm volatile("s_waitcnt lgkmcnt(" #n ")" ::: "memory")
; #define PG8_BAR __builtin_amdgcn_s_barrier()
; #define PG8_SCHED __builtin_amdgcn_sched_barrier(0)
; template <class Epi>
; __device__ __forceinline__ void gemm_phase(LAS unsigned char* lds, const Gemm g, const StaticOrder& S, const Epi& E) {
;     ...
;             PG8_LDB(B0, 1, 0); PG8_LDB(B1, 1, 1); PG8_SCHED; PG8_LDA(At, 1, 0); PG8_STAGE(PG8_SA(0, 1), a2 + hstep, voffA);
;             PG8_WAIT_V(8); PG8_WAIT_L(0); PG8_BAR; PG8_MMA(0, 0, At, B0); PG8_MMA(0, 1, At, B1); PG8_BAR; PG8_SCHED;
;             PG8_LDA(At, 1, 1); PG8_STAGE(PG8_SB(1, 0), b3, voffB); PG8_STAGE(PG8_SB(1, 1), b3 + hstep, voffB); PG8_STAGE(PG8_SA(1, 0), a3, voffA);
;             PG8_WAIT_V(8); PG8_WAIT_L(0); PG8_BAR; PG8_MMA(1, 0, At, B0); PG8_MMA(1, 1, At, B1); PG8_BAR; PG8_SCHED;
;         }
;         if (wr == 0) PG8_BAR;
	s_setprio 0
	s_add_i32 s64, 0, 0x18000
	s_add_i32 s65, 0, 0x1c000
	v_add_u32_e32 v166, s64, v160
	v_add_u32_e32 v184, s65, v160
	ds_read_b128 v[130:133], v166
	ds_read_b128 v[134:137], v166 offset:1024
	ds_read_b128 v[154:157], v166 offset:2048
	ds_read_b128 v[166:169], v166 offset:3072
	ds_read_b128 v[172:175], v184
	ds_read_b128 v[176:179], v184 offset:1024
	ds_read_b128 v[180:183], v184 offset:2048
	ds_read_b128 v[184:187], v184 offset:3072
	s_add_u32 s42, s42, 0x40000
	s_addc_u32 s43, s43, 0
	s_mov_b32 m0, s47
	ds_read_b128 v[188:191], v164 offset:32768
	ds_read_b128 v[192:195], v164 offset:33792
	ds_read_b128 v[196:199], v164 offset:34816
	ds_read_b128 v[200:203], v164 offset:35840
	ds_read_b128 v[204:207], v164 offset:36864
	ds_read_b128 v[208:211], v164 offset:37888
	ds_read_b128 v[212:215], v164 offset:38912
	ds_read_b128 v[216:219], v164 offset:39936
	global_load_lds_dwordx4 v138, s[42:43]
	s_mov_b32 m0, s48
	s_nop 0
	global_load_lds_dwordx4 v142, s[42:43]
	s_waitcnt vmcnt(8)
	s_waitcnt lgkmcnt(0)
	s_setprio 1
	s_barrier
	v_mfma_f32_16x16x32_bf16 v[126:129], v[130:133], v[188:191], v[126:129]
	v_mfma_f32_16x16x32_bf16 v[106:109], v[154:157], v[196:199], v[106:109]
	v_mfma_f32_16x16x32_bf16 v[94:97], v[130:133], v[204:207], v[94:97]
	v_mfma_f32_16x16x32_bf16 v[74:77], v[154:157], v[212:215], v[74:77]
	v_mfma_f32_16x16x32_bf16 v[122:125], v[154:157], v[188:191], v[122:125]
	v_mfma_f32_16x16x32_bf16 v[110:113], v[130:133], v[196:199], v[110:113]
	v_mfma_f32_16x16x32_bf16 v[90:93], v[154:157], v[204:207], v[90:93]
	v_mfma_f32_16x16x32_bf16 v[78:81], v[130:133], v[212:215], v[78:81]
	v_mfma_f32_16x16x32_bf16 v[126:129], v[134:137], v[192:195], v[126:129]
	v_mfma_f32_16x16x32_bf16 v[106:109], v[166:169], v[200:203], v[106:109]
	v_mfma_f32_16x16x32_bf16 v[94:97], v[134:137], v[208:211], v[94:97]
	v_mfma_f32_16x16x32_bf16 v[74:77], v[166:169], v[216:219], v[74:77]
	v_mfma_f32_16x16x32_bf16 v[122:125], v[166:169], v[192:195], v[122:125]
	v_mfma_f32_16x16x32_bf16 v[110:113], v[134:137], v[200:203], v[110:113]
	v_mfma_f32_16x16x32_bf16 v[90:93], v[166:169], v[208:211], v[90:93]
	v_mfma_f32_16x16x32_bf16 v[78:81], v[134:137], v[216:219], v[78:81]
	v_mfma_f32_16x16x32_bf16 v[118:121], v[172:175], v[188:191], v[118:121]
	v_mfma_f32_16x16x32_bf16 v[98:101], v[180:183], v[196:199], v[98:101]
	v_mfma_f32_16x16x32_bf16 v[86:89], v[172:175], v[204:207], v[86:89]
	v_mfma_f32_16x16x32_bf16 v[66:69], v[180:183], v[212:215], v[66:69]
	v_mfma_f32_16x16x32_bf16 v[114:117], v[180:183], v[188:191], v[114:117]
	v_mfma_f32_16x16x32_bf16 v[102:105], v[172:175], v[196:199], v[102:105]
	v_mfma_f32_16x16x32_bf16 v[82:85], v[180:183], v[204:207], v[82:85]
	v_mfma_f32_16x16x32_bf16 v[70:73], v[172:175], v[212:215], v[70:73]
	v_mfma_f32_16x16x32_bf16 v[118:121], v[176:179], v[192:195], v[118:121]
	v_mfma_f32_16x16x32_bf16 v[98:101], v[184:187], v[200:203], v[98:101]
	v_mfma_f32_16x16x32_bf16 v[86:89], v[176:179], v[208:211], v[86:89]
	v_mfma_f32_16x16x32_bf16 v[66:69], v[184:187], v[216:219], v[66:69]
	v_mfma_f32_16x16x32_bf16 v[114:117], v[184:187], v[192:195], v[114:117]
	v_mfma_f32_16x16x32_bf16 v[102:105], v[176:179], v[200:203], v[102:105]
	v_mfma_f32_16x16x32_bf16 v[82:85], v[184:187], v[208:211], v[82:85]
	v_mfma_f32_16x16x32_bf16 v[70:73], v[176:179], v[216:219], v[70:73]
	s_barrier
	s_setprio 0
	s_add_i32 s42, s64, s44
	s_mov_b32 m0, s42
	ds_read_b128 v[188:191], v164 offset:49152
	ds_read_b128 v[192:195], v164 offset:50176
	ds_read_b128 v[196:199], v164 offset:51200
	ds_read_b128 v[200:203], v164 offset:52224
	ds_read_b128 v[204:207], v164 offset:53248
	ds_read_b128 v[208:211], v164 offset:54272
	ds_read_b128 v[212:215], v164 offset:55296
	ds_read_b128 v[216:219], v164 offset:56320
	global_load_lds_dwordx4 v140, s[98:99]
	s_add_i32 m0, s42, 0x2000
	s_add_u32 s40, s40, 0x40080
	s_addc_u32 s41, s41, 0
	s_add_i32 s42, s65, s44
	global_load_lds_dwordx4 v144, s[98:99]
	s_mov_b32 m0, s42
	s_nop 0
	global_load_lds_dwordx4 v140, s[40:41]
	s_add_i32 m0, s42, 0x2000
	s_nop 0
	global_load_lds_dwordx4 v144, s[40:41]
	s_mov_b32 m0, s50
	s_nop 0
	global_load_lds_dwordx4 v138, s[100:101]
	s_mov_b32 m0, s51
	s_nop 0
	global_load_lds_dwordx4 v142, s[100:101]
	s_waitcnt vmcnt(8)
	s_waitcnt lgkmcnt(0)
	s_setprio 1
	s_barrier
	v_mfma_f32_16x16x32_bf16 v[62:65], v[130:133], v[188:191], v[62:65]
	v_mfma_f32_16x16x32_bf16 v[42:45], v[154:157], v[196:199], v[42:45]
	v_mfma_f32_16x16x32_bf16 v[30:33], v[130:133], v[204:207], v[30:33]
	v_mfma_f32_16x16x32_bf16 v[10:13], v[154:157], v[212:215], v[10:13]
	v_mfma_f32_16x16x32_bf16 v[58:61], v[154:157], v[188:191], v[58:61]
	v_mfma_f32_16x16x32_bf16 v[46:49], v[130:133], v[196:199], v[46:49]
	v_mfma_f32_16x16x32_bf16 v[26:29], v[154:157], v[204:207], v[26:29]
	v_mfma_f32_16x16x32_bf16 v[14:17], v[130:133], v[212:215], v[14:17]
	v_mfma_f32_16x16x32_bf16 v[62:65], v[134:137], v[192:195], v[62:65]
	v_mfma_f32_16x16x32_bf16 v[42:45], v[166:169], v[200:203], v[42:45]
	v_mfma_f32_16x16x32_bf16 v[30:33], v[134:137], v[208:211], v[30:33]
	v_mfma_f32_16x16x32_bf16 v[10:13], v[166:169], v[216:219], v[10:13]
	v_mfma_f32_16x16x32_bf16 v[58:61], v[166:169], v[192:195], v[58:61]
	v_mfma_f32_16x16x32_bf16 v[46:49], v[134:137], v[200:203], v[46:49]
	v_mfma_f32_16x16x32_bf16 v[26:29], v[166:169], v[208:211], v[26:29]
	v_mfma_f32_16x16x32_bf16 v[14:17], v[134:137], v[216:219], v[14:17]
	v_mfma_f32_16x16x32_bf16 v[54:57], v[172:175], v[188:191], v[54:57]
	v_mfma_f32_16x16x32_bf16 v[34:37], v[180:183], v[196:199], v[34:37]
	v_mfma_f32_16x16x32_bf16 v[22:25], v[172:175], v[204:207], v[22:25]
	v_mfma_f32_16x16x32_bf16 v[2:5], v[180:183], v[212:215], v[2:5]
	v_mfma_f32_16x16x32_bf16 v[50:53], v[180:183], v[188:191], v[50:53]
	v_mfma_f32_16x16x32_bf16 v[38:41], v[172:175], v[196:199], v[38:41]
	v_mfma_f32_16x16x32_bf16 v[18:21], v[180:183], v[204:207], v[18:21]
	v_mfma_f32_16x16x32_bf16 v[6:9], v[172:175], v[212:215], v[6:9]
	v_mfma_f32_16x16x32_bf16 v[54:57], v[176:179], v[192:195], v[54:57]
	v_mfma_f32_16x16x32_bf16 v[34:37], v[184:187], v[200:203], v[34:37]
	v_mfma_f32_16x16x32_bf16 v[22:25], v[176:179], v[208:211], v[22:25]
	v_mfma_f32_16x16x32_bf16 v[2:5], v[184:187], v[216:219], v[2:5]
	v_mfma_f32_16x16x32_bf16 v[50:53], v[184:187], v[192:195], v[50:53]
	v_mfma_f32_16x16x32_bf16 v[38:41], v[176:179], v[200:203], v[38:41]
	v_mfma_f32_16x16x32_bf16 v[18:21], v[184:187], v[208:211], v[18:21]
	v_mfma_f32_16x16x32_bf16 v[6:9], v[176:179], v[216:219], v[6:9]
	s_barrier
	s_setprio 0
	s_add_i32 s63, s63, 2
	s_add_u32 s38, s38, 0x100
	s_addc_u32 s39, s39, 0
	s_add_u32 s61, s61, 0x100
	s_addc_u32 s62, s62, 0
	s_cmp_gt_u32 s63, 13
	s_cbranch_scc0 .LBB0_785
	s_and_b64 vcc, exec, s[14:15]
	s_cbranch_vccz .LBB0_788
	s_barrier

; #define PG8_STAGE(bufoff, gbase, voff) do { _Pragma("unroll") for (int _i = 0; _i < 2; ++_i) \
;         __builtin_amdgcn_global_load_lds((const unsigned*)((const char*)(gbase) + (voff)[_i]), (LAS unsigned*)(lds + (bufoff) + ldsw + _i * 8192), 16, 0, 0); } while (0)
; #define PG8_LDA(dst, b, h) do { _Pragma("unroll") for (int m = 0; m < 4; ++m) _Pragma("unroll") for (int k = 0; k < 2; ++k) dst[m][k] = *(const LAS bf16x8*)(lds + PG8_SA(b, h) + aoff + m * 2048 + k * 1024); } while (0)
; #define PG8_LDB(dst, b, h) do { _Pragma("unroll") for (int n = 0; n < 2; ++n) _Pragma("unroll") for (int k = 0; k < 2; ++k) dst[n][k] = *(const LAS bf16x8*)(lds + PG8_SB(b, h) + boff + n * 2048 + k * 1024); } while (0)
; #define PG8_MMA(ai, bj, At, Bt) do { __builtin_amdgcn_s_setprio(1); _Pragma("unroll") for (int m = 0; m < 4; ++m) _Pragma("unroll") for (int n = 0; n < 2; ++n) _Pragma("unroll") for (int k = 0; k < 2; ++k) \
;         acc[ai][bj][m][n] = __builtin_amdgcn_mfma_f32_16x16x32_bf16(Bt[n][k], At[m][k], acc[ai][bj][m][n], 0, 0, 0); __builtin_amdgcn_s_setprio(0); } while (0)
; #define PG8_WAIT_V(n) asm volatile("s_waitcnt vmcnt(" #n ")" ::: "memory")
; #define PG8_WAIT_L(n) asm volatile("s_waitcnt lgkmcnt(" #n ")" ::: "memory")
; #define PG8_BAR __builtin_amdgcn_s_barrier()
; template <class Epi>
; __device__ __forceinline__ void gemm_phase(LAS unsigned char* lds, const Gemm g, const StaticOrder& S, const Epi& E) {
;     ...
;         for (int t = 0; t < nt; t += 2) {
;             const bool last = (t == nt - 2);
;             const char* a1 = cA + (size_t)(t + 1) * kstep;
;             const char* a2 = last ? nA : cA + (size_t)(t + 2) * kstep; const char* b2 = last ? nB : cB + (size_t)(t + 2) * kstep;
;             const char* a3 = a2 + kstep; const char* b3 = b2 + kstep;
;             if constexpr (Epi::MIDK > 0) { if (t == Epi::MIDK) E.mid(acc, cur, wr, wc, fr, fq); }
;             PG8_LDB(B0, 0, 0); PG8_LDB(B1, 0, 1); PG8_SCHED; PG8_LDA(At, 0, 0); PG8_STAGE(PG8_SA(1, 1), a1 + hstep, voffA);
;             PG8_WAIT_V(8); PG8_WAIT_L(0); PG8_BAR; PG8_MMA(0, 0, At, B0); PG8_MMA(0, 1, At, B1); PG8_BAR; PG8_SCHED;
;             PG8_LDA(At, 0, 1); PG8_STAGE(PG8_SB(0, 0), b2, voffB); PG8_STAGE(PG8_SB(0, 1), b2 + hstep, voffB); PG8_STAGE(PG8_SA(0, 0), a2, voffA);
;             PG8_WAIT_V(8); PG8_WAIT_L(0); PG8_BAR; PG8_MMA(1, 0, At, B0); PG8_MMA(1, 1, At, B1); PG8_BAR; PG8_SCHED;
.LBB0_884:
	ds_read_b128 v[158:161], v150
	ds_read_b128 v[162:165], v150 offset:1024
	ds_read_b128 v[166:169], v150 offset:2048
	ds_read_b128 v[174:177], v150 offset:3072
	ds_read_b128 v[178:181], v151
	ds_read_b128 v[182:185], v151 offset:1024
	ds_read_b128 v[186:189], v151 offset:2048
	ds_read_b128 v[190:193], v151 offset:3072
	s_add_u32 s46, s44, 0xfffc0080
	s_addc_u32 s47, s45, -1
	s_cmp_eq_u32 s67, 12
	s_cselect_b32 s49, s62, s47
	s_cselect_b32 s48, s63, s46
	s_cselect_b32 s47, s23, s66
	s_cselect_b32 s46, s64, s65
	s_add_i32 m0, s41, 0xc000
	ds_read_b128 v[194:197], v152
	ds_read_b128 v[198:201], v152 offset:1024
	ds_read_b128 v[202:205], v152 offset:2048
	ds_read_b128 v[206:209], v152 offset:3072
	ds_read_b128 v[210:213], v152 offset:4096
	ds_read_b128 v[214:217], v152 offset:5120
	ds_read_b128 v[218:221], v152 offset:6144
	ds_read_b128 v[222:225], v152 offset:7168
	global_load_lds_dwordx4 v140, s[44:45]
	s_add_i32 m0, s41, 0xe000
	s_nop 0
	global_load_lds_dwordx4 v142, s[44:45]
	s_waitcnt vmcnt(8)
	s_waitcnt lgkmcnt(0)
	s_setprio 1
	s_barrier
	v_mfma_f32_16x16x32_bf16 v[126:129], v[158:161], v[194:197], v[126:129]
	v_mfma_f32_16x16x32_bf16 v[102:105], v[166:169], v[202:205], v[102:105]
	v_mfma_f32_16x16x32_bf16 v[94:97], v[158:161], v[210:213], v[94:97]
	v_mfma_f32_16x16x32_bf16 v[70:73], v[166:169], v[218:221], v[70:73]
	v_mfma_f32_16x16x32_bf16 v[118:121], v[166:169], v[194:197], v[118:121]
	v_mfma_f32_16x16x32_bf16 v[110:113], v[158:161], v[202:205], v[110:113]
	v_mfma_f32_16x16x32_bf16 v[86:89], v[166:169], v[210:213], v[86:89]
	v_mfma_f32_16x16x32_bf16 v[78:81], v[158:161], v[218:221], v[78:81]
	v_mfma_f32_16x16x32_bf16 v[126:129], v[162:165], v[198:201], v[126:129]
	v_mfma_f32_16x16x32_bf16 v[102:105], v[174:177], v[206:209], v[102:105]
	v_mfma_f32_16x16x32_bf16 v[94:97], v[162:165], v[214:217], v[94:97]
	v_mfma_f32_16x16x32_bf16 v[70:73], v[174:177], v[222:225], v[70:73]
	v_mfma_f32_16x16x32_bf16 v[118:121], v[174:177], v[198:201], v[118:121]
	v_mfma_f32_16x16x32_bf16 v[110:113], v[162:165], v[206:209], v[110:113]
	v_mfma_f32_16x16x32_bf16 v[86:89], v[174:177], v[214:217], v[86:89]
	v_mfma_f32_16x16x32_bf16 v[78:81], v[162:165], v[222:225], v[78:81]
	v_mfma_f32_16x16x32_bf16 v[122:125], v[178:181], v[194:197], v[122:125]
	v_mfma_f32_16x16x32_bf16 v[98:101], v[186:189], v[202:205], v[98:101]
	v_mfma_f32_16x16x32_bf16 v[90:93], v[178:181], v[210:213], v[90:93]
	v_mfma_f32_16x16x32_bf16 v[66:69], v[186:189], v[218:221], v[66:69]
	v_mfma_f32_16x16x32_bf16 v[114:117], v[186:189], v[194:197], v[114:117]
	v_mfma_f32_16x16x32_bf16 v[106:109], v[178:181], v[202:205], v[106:109]
	v_mfma_f32_16x16x32_bf16 v[82:85], v[186:189], v[210:213], v[82:85]
	v_mfma_f32_16x16x32_bf16 v[74:77], v[178:181], v[218:221], v[74:77]
	v_mfma_f32_16x16x32_bf16 v[122:125], v[182:185], v[198:201], v[122:125]
	v_mfma_f32_16x16x32_bf16 v[98:101], v[190:193], v[206:209], v[98:101]
	v_mfma_f32_16x16x32_bf16 v[90:93], v[182:185], v[214:217], v[90:93]
	v_mfma_f32_16x16x32_bf16 v[66:69], v[190:193], v[222:225], v[66:69]
	v_mfma_f32_16x16x32_bf16 v[114:117], v[190:193], v[198:201], v[114:117]
	v_mfma_f32_16x16x32_bf16 v[106:109], v[182:185], v[206:209], v[106:109]
	v_mfma_f32_16x16x32_bf16 v[82:85], v[190:193], v[214:217], v[82:85]
	v_mfma_f32_16x16x32_bf16 v[74:77], v[182:185], v[222:225], v[74:77]
	s_barrier
	s_setprio 0
	s_add_u32 s98, s46, s8
	s_addc_u32 s99, s47, s9
	s_add_u32 s100, s48, s8
	s_addc_u32 s101, s49, s9
	s_add_i32 s68, s58, s6
	s_mov_b32 m0, s68
	ds_read_b128 v[194:197], v152 offset:16384
	ds_read_b128 v[198:201], v152 offset:17408
	ds_read_b128 v[202:205], v152 offset:18432
	ds_read_b128 v[206:209], v152 offset:19456
	ds_read_b128 v[210:213], v152 offset:20480
	ds_read_b128 v[214:217], v152 offset:21504
	ds_read_b128 v[218:221], v152 offset:22528
	ds_read_b128 v[222:225], v152 offset:23552
	global_load_lds_dwordx4 v132, s[46:47]
	s_add_i32 m0, s68, 0x2000
	s_add_u32 s68, s46, 0x40000
	s_addc_u32 s69, s47, 0
	s_add_i32 s76, s59, s6
	global_load_lds_dwordx4 v136, s[46:47]
	s_mov_b32 m0, s76
	s_nop 0
	global_load_lds_dwordx4 v132, s[68:69]
	s_add_i32 m0, s76, 0x2000
	s_nop 0
	global_load_lds_dwordx4 v136, s[68:69]
	s_mov_b32 m0, s41
	s_nop 0
	global_load_lds_dwordx4 v130, s[48:49]
	s_mov_b32 m0, s43
	s_nop 0
	global_load_lds_dwordx4 v134, s[48:49]
	s_waitcnt vmcnt(8)
	s_waitcnt lgkmcnt(0)
	s_setprio 1
	s_barrier
	v_mfma_f32_16x16x32_bf16 v[62:65], v[158:161], v[194:197], v[62:65]
	v_mfma_f32_16x16x32_bf16 v[38:41], v[166:169], v[202:205], v[38:41]
	v_mfma_f32_16x16x32_bf16 v[30:33], v[158:161], v[210:213], v[30:33]
	v_mfma_f32_16x16x32_bf16 v[6:9], v[166:169], v[218:221], v[6:9]
	v_mfma_f32_16x16x32_bf16 v[54:57], v[166:169], v[194:197], v[54:57]
	v_mfma_f32_16x16x32_bf16 v[46:49], v[158:161], v[202:205], v[46:49]
	v_mfma_f32_16x16x32_bf16 v[22:25], v[166:169], v[210:213], v[22:25]
	v_mfma_f32_16x16x32_bf16 v[14:17], v[158:161], v[218:221], v[14:17]
	v_mfma_f32_16x16x32_bf16 v[62:65], v[162:165], v[198:201], v[62:65]
	v_mfma_f32_16x16x32_bf16 v[38:41], v[174:177], v[206:209], v[38:41]
	v_mfma_f32_16x16x32_bf16 v[30:33], v[162:165], v[214:217], v[30:33]
	v_mfma_f32_16x16x32_bf16 v[6:9], v[174:177], v[222:225], v[6:9]
	v_mfma_f32_16x16x32_bf16 v[54:57], v[174:177], v[198:201], v[54:57]
	v_mfma_f32_16x16x32_bf16 v[46:49], v[162:165], v[206:209], v[46:49]
	v_mfma_f32_16x16x32_bf16 v[22:25], v[174:177], v[214:217], v[22:25]
	v_mfma_f32_16x16x32_bf16 v[14:17], v[162:165], v[222:225], v[14:17]
	v_mfma_f32_16x16x32_bf16 v[58:61], v[178:181], v[194:197], v[58:61]
	v_mfma_f32_16x16x32_bf16 v[34:37], v[186:189], v[202:205], v[34:37]
	v_mfma_f32_16x16x32_bf16 v[26:29], v[178:181], v[210:213], v[26:29]
	v_mfma_f32_16x16x32_bf16 v[2:5], v[186:189], v[218:221], v[2:5]
	v_mfma_f32_16x16x32_bf16 v[50:53], v[186:189], v[194:197], v[50:53]
	v_mfma_f32_16x16x32_bf16 v[42:45], v[178:181], v[202:205], v[42:45]
	v_mfma_f32_16x16x32_bf16 v[18:21], v[186:189], v[210:213], v[18:21]
	v_mfma_f32_16x16x32_bf16 v[10:13], v[178:181], v[218:221], v[10:13]
	v_mfma_f32_16x16x32_bf16 v[58:61], v[182:185], v[198:201], v[58:61]
	v_mfma_f32_16x16x32_bf16 v[34:37], v[190:193], v[206:209], v[34:37]
	v_mfma_f32_16x16x32_bf16 v[26:29], v[182:185], v[214:217], v[26:29]
	v_mfma_f32_16x16x32_bf16 v[2:5], v[190:193], v[222:225], v[2:5]
	v_mfma_f32_16x16x32_bf16 v[50:53], v[190:193], v[198:201], v[50:53]
	v_mfma_f32_16x16x32_bf16 v[42:45], v[182:185], v[206:209], v[42:45]
	v_mfma_f32_16x16x32_bf16 v[18:21], v[190:193], v[214:217], v[18:21]
	v_mfma_f32_16x16x32_bf16 v[10:13], v[182:185], v[222:225], v[10:13]
	s_barrier
; #define PG8_STAGE(bufoff, gbase, voff) do { _Pragma("unroll") for (int _i = 0; _i < 2; ++_i) \
;         __builtin_amdgcn_global_load_lds((const unsigned*)((const char*)(gbase) + (voff)[_i]), (LAS unsigned*)(lds + (bufoff) + ldsw + _i * 8192), 16, 0, 0); } while (0)
; #define PG8_LDA(dst, b, h) do { _Pragma("unroll") for (int m = 0; m < 4; ++m) _Pragma("unroll") for (int k = 0; k < 2; ++k) dst[m][k] = *(const LAS bf16x8*)(lds + PG8_SA(b, h) + aoff + m * 2048 + k * 1024); } while (0)
; #define PG8_LDB(dst, b, h) do { _Pragma("unroll") for (int n = 0; n < 2; ++n) _Pragma("unroll") for (int k = 0; k < 2; ++k) dst[n][k] = *(const LAS bf16x8*)(lds + PG8_SB(b, h) + boff + n * 2048 + k * 1024); } while (0)
; #define PG8_MMA(ai, bj, At, Bt) do { __builtin_amdgcn_s_setprio(1); _Pragma("unroll") for (int m = 0; m < 4; ++m) _Pragma("unroll") for (int n = 0; n < 2; ++n) _Pragma("unroll") for (int k = 0; k < 2; ++k) \
;         acc[ai][bj][m][n] = __builtin_amdgcn_mfma_f32_16x16x32_bf16(Bt[n][k], At[m][k], acc[ai][bj][m][n], 0, 0, 0); __builtin_amdgcn_s_setprio(0); } while (0)
; #define PG8_WAIT_V(n) asm volatile("s_waitcnt vmcnt(" #n ")" ::: "memory")
; #define PG8_WAIT_L(n) asm volatile("s_waitcnt lgkmcnt(" #n ")" ::: "memory")
; #define PG8_BAR __builtin_amdgcn_s_barrier()
; #define PG8_SCHED __builtin_amdgcn_sched_barrier(0)
; template <class Epi>
; __device__ __forceinline__ void gemm_phase(LAS unsigned char* lds, const Gemm g, const StaticOrder& S, const Epi& E) {
;     ...
;             PG8_LDB(B0, 1, 0); PG8_LDB(B1, 1, 1); PG8_SCHED; PG8_LDA(At, 1, 0); PG8_STAGE(PG8_SA(0, 1), a2 + hstep, voffA);
;             PG8_WAIT_V(8); PG8_WAIT_L(0); PG8_BAR; PG8_MMA(0, 0, At, B0); PG8_MMA(0, 1, At, B1); PG8_BAR; PG8_SCHED;
;             PG8_LDA(At, 1, 1); PG8_STAGE(PG8_SB(1, 0), b3, voffB); PG8_STAGE(PG8_SB(1, 1), b3 + hstep, voffB); PG8_STAGE(PG8_SA(1, 0), a3, voffA);
;             PG8_WAIT_V(8); PG8_WAIT_L(0); PG8_BAR; PG8_MMA(1, 0, At, B0); PG8_MMA(1, 1, At, B1); PG8_BAR; PG8_SCHED;
;         }
;         if (wr == 0) PG8_BAR;
	s_setprio 0
	s_add_i32 s68, 0, 0x18000
	s_add_i32 s69, 0, 0x1c000
	v_add_u32_e32 v174, s68, v148
	v_add_u32_e32 v190, s69, v148
	ds_read_b128 v[158:161], v174
	ds_read_b128 v[162:165], v174 offset:1024
	ds_read_b128 v[166:169], v174 offset:2048
	ds_read_b128 v[174:177], v174 offset:3072
	ds_read_b128 v[178:181], v190
	ds_read_b128 v[182:185], v190 offset:1024
	ds_read_b128 v[186:189], v190 offset:2048
	ds_read_b128 v[190:193], v190 offset:3072
	s_add_u32 s48, s48, 0x40000
	s_addc_u32 s49, s49, 0
	s_mov_b32 m0, s51
	ds_read_b128 v[194:197], v152 offset:32768
	ds_read_b128 v[198:201], v152 offset:33792
	ds_read_b128 v[202:205], v152 offset:34816
	ds_read_b128 v[206:209], v152 offset:35840
	ds_read_b128 v[210:213], v152 offset:36864
	ds_read_b128 v[214:217], v152 offset:37888
	ds_read_b128 v[218:221], v152 offset:38912
	ds_read_b128 v[222:225], v152 offset:39936
	global_load_lds_dwordx4 v130, s[48:49]
	s_mov_b32 m0, s52
	s_nop 0
	global_load_lds_dwordx4 v134, s[48:49]
	s_waitcnt vmcnt(8)
	s_waitcnt lgkmcnt(0)
	s_setprio 1
	s_barrier
	v_mfma_f32_16x16x32_bf16 v[126:129], v[158:161], v[194:197], v[126:129]
	v_mfma_f32_16x16x32_bf16 v[102:105], v[166:169], v[202:205], v[102:105]
	v_mfma_f32_16x16x32_bf16 v[94:97], v[158:161], v[210:213], v[94:97]
	v_mfma_f32_16x16x32_bf16 v[70:73], v[166:169], v[218:221], v[70:73]
	v_mfma_f32_16x16x32_bf16 v[118:121], v[166:169], v[194:197], v[118:121]
	v_mfma_f32_16x16x32_bf16 v[110:113], v[158:161], v[202:205], v[110:113]
	v_mfma_f32_16x16x32_bf16 v[86:89], v[166:169], v[210:213], v[86:89]
	v_mfma_f32_16x16x32_bf16 v[78:81], v[158:161], v[218:221], v[78:81]
	v_mfma_f32_16x16x32_bf16 v[126:129], v[162:165], v[198:201], v[126:129]
	v_mfma_f32_16x16x32_bf16 v[102:105], v[174:177], v[206:209], v[102:105]
	v_mfma_f32_16x16x32_bf16 v[94:97], v[162:165], v[214:217], v[94:97]
	v_mfma_f32_16x16x32_bf16 v[70:73], v[174:177], v[222:225], v[70:73]
	v_mfma_f32_16x16x32_bf16 v[118:121], v[174:177], v[198:201], v[118:121]
	v_mfma_f32_16x16x32_bf16 v[110:113], v[162:165], v[206:209], v[110:113]
	v_mfma_f32_16x16x32_bf16 v[86:89], v[174:177], v[214:217], v[86:89]
	v_mfma_f32_16x16x32_bf16 v[78:81], v[162:165], v[222:225], v[78:81]
	v_mfma_f32_16x16x32_bf16 v[122:125], v[178:181], v[194:197], v[122:125]
	v_mfma_f32_16x16x32_bf16 v[98:101], v[186:189], v[202:205], v[98:101]
	v_mfma_f32_16x16x32_bf16 v[90:93], v[178:181], v[210:213], v[90:93]
	v_mfma_f32_16x16x32_bf16 v[66:69], v[186:189], v[218:221], v[66:69]
	v_mfma_f32_16x16x32_bf16 v[114:117], v[186:189], v[194:197], v[114:117]
	v_mfma_f32_16x16x32_bf16 v[106:109], v[178:181], v[202:205], v[106:109]
	v_mfma_f32_16x16x32_bf16 v[82:85], v[186:189], v[210:213], v[82:85]
	v_mfma_f32_16x16x32_bf16 v[74:77], v[178:181], v[218:221], v[74:77]
	v_mfma_f32_16x16x32_bf16 v[122:125], v[182:185], v[198:201], v[122:125]
	v_mfma_f32_16x16x32_bf16 v[98:101], v[190:193], v[206:209], v[98:101]
	v_mfma_f32_16x16x32_bf16 v[90:93], v[182:185], v[214:217], v[90:93]
	v_mfma_f32_16x16x32_bf16 v[66:69], v[190:193], v[222:225], v[66:69]
	v_mfma_f32_16x16x32_bf16 v[114:117], v[190:193], v[198:201], v[114:117]
	v_mfma_f32_16x16x32_bf16 v[106:109], v[182:185], v[206:209], v[106:109]
	v_mfma_f32_16x16x32_bf16 v[82:85], v[190:193], v[214:217], v[82:85]
	v_mfma_f32_16x16x32_bf16 v[74:77], v[182:185], v[222:225], v[74:77]
	s_barrier
	s_setprio 0
	s_add_i32 s48, s68, s6
	s_mov_b32 m0, s48
	ds_read_b128 v[194:197], v152 offset:49152
	ds_read_b128 v[198:201], v152 offset:50176
	ds_read_b128 v[202:205], v152 offset:51200
	ds_read_b128 v[206:209], v152 offset:52224
	ds_read_b128 v[210:213], v152 offset:53248
	ds_read_b128 v[214:217], v152 offset:54272
	ds_read_b128 v[218:221], v152 offset:55296
	ds_read_b128 v[222:225], v152 offset:56320
	global_load_lds_dwordx4 v132, s[98:99]
	s_add_i32 m0, s48, 0x2000
	s_add_u32 s46, s46, 0x40080
	s_addc_u32 s47, s47, 0
	s_add_i32 s48, s69, s6
	global_load_lds_dwordx4 v136, s[98:99]
	s_mov_b32 m0, s48
	s_nop 0
	global_load_lds_dwordx4 v132, s[46:47]
	s_add_i32 m0, s48, 0x2000
	s_nop 0
	global_load_lds_dwordx4 v136, s[46:47]
	s_mov_b32 m0, s53
	s_nop 0
	global_load_lds_dwordx4 v130, s[100:101]
	s_mov_b32 m0, s54
	s_nop 0
	global_load_lds_dwordx4 v134, s[100:101]
	s_waitcnt vmcnt(8)
	s_waitcnt lgkmcnt(0)
	s_setprio 1
	s_barrier
	v_mfma_f32_16x16x32_bf16 v[62:65], v[158:161], v[194:197], v[62:65]
	v_mfma_f32_16x16x32_bf16 v[38:41], v[166:169], v[202:205], v[38:41]
	v_mfma_f32_16x16x32_bf16 v[30:33], v[158:161], v[210:213], v[30:33]
	v_mfma_f32_16x16x32_bf16 v[6:9], v[166:169], v[218:221], v[6:9]
	v_mfma_f32_16x16x32_bf16 v[54:57], v[166:169], v[194:197], v[54:57]
	v_mfma_f32_16x16x32_bf16 v[46:49], v[158:161], v[202:205], v[46:49]
	v_mfma_f32_16x16x32_bf16 v[22:25], v[166:169], v[210:213], v[22:25]
	v_mfma_f32_16x16x32_bf16 v[14:17], v[158:161], v[218:221], v[14:17]
	v_mfma_f32_16x16x32_bf16 v[62:65], v[162:165], v[198:201], v[62:65]
	v_mfma_f32_16x16x32_bf16 v[38:41], v[174:177], v[206:209], v[38:41]
	v_mfma_f32_16x16x32_bf16 v[30:33], v[162:165], v[214:217], v[30:33]
	v_mfma_f32_16x16x32_bf16 v[6:9], v[174:177], v[222:225], v[6:9]
	v_mfma_f32_16x16x32_bf16 v[54:57], v[174:177], v[198:201], v[54:57]
	v_mfma_f32_16x16x32_bf16 v[46:49], v[162:165], v[206:209], v[46:49]
	v_mfma_f32_16x16x32_bf16 v[22:25], v[174:177], v[214:217], v[22:25]
	v_mfma_f32_16x16x32_bf16 v[14:17], v[162:165], v[222:225], v[14:17]
	v_mfma_f32_16x16x32_bf16 v[58:61], v[178:181], v[194:197], v[58:61]
	v_mfma_f32_16x16x32_bf16 v[34:37], v[186:189], v[202:205], v[34:37]
	v_mfma_f32_16x16x32_bf16 v[26:29], v[178:181], v[210:213], v[26:29]
	v_mfma_f32_16x16x32_bf16 v[2:5], v[186:189], v[218:221], v[2:5]
	v_mfma_f32_16x16x32_bf16 v[50:53], v[186:189], v[194:197], v[50:53]
	v_mfma_f32_16x16x32_bf16 v[42:45], v[178:181], v[202:205], v[42:45]
	v_mfma_f32_16x16x32_bf16 v[18:21], v[186:189], v[210:213], v[18:21]
	v_mfma_f32_16x16x32_bf16 v[10:13], v[178:181], v[218:221], v[10:13]
	v_mfma_f32_16x16x32_bf16 v[58:61], v[182:185], v[198:201], v[58:61]
	v_mfma_f32_16x16x32_bf16 v[34:37], v[190:193], v[206:209], v[34:37]
	v_mfma_f32_16x16x32_bf16 v[26:29], v[182:185], v[214:217], v[26:29]
	v_mfma_f32_16x16x32_bf16 v[2:5], v[190:193], v[222:225], v[2:5]
	v_mfma_f32_16x16x32_bf16 v[50:53], v[190:193], v[198:201], v[50:53]
	v_mfma_f32_16x16x32_bf16 v[42:45], v[182:185], v[206:209], v[42:45]
	v_mfma_f32_16x16x32_bf16 v[18:21], v[190:193], v[214:217], v[18:21]
	v_mfma_f32_16x16x32_bf16 v[10:13], v[182:185], v[222:225], v[10:13]
	s_barrier
	s_setprio 0
	s_add_i32 s67, s67, 2
	s_add_u32 s44, s44, 0x100
	s_addc_u32 s45, s45, 0
	s_add_u32 s65, s65, 0x100
	s_addc_u32 s66, s66, 0
	s_cmp_gt_u32 s67, 13
	s_cbranch_scc0 .LBB0_884
	s_and_b64 vcc, exec, s[14:15]
	s_cbranch_vccz .LBB0_887
	s_barrier

; #define PG8_STAGE(bufoff, gbase, voff) do { _Pragma("unroll") for (int _i = 0; _i < 2; ++_i) \
;         __builtin_amdgcn_global_load_lds((const unsigned*)((const char*)(gbase) + (voff)[_i]), (LAS unsigned*)(lds + (bufoff) + ldsw + _i * 8192), 16, 0, 0); } while (0)
; #define PG8_LDA(dst, b, h) do { _Pragma("unroll") for (int m = 0; m < 4; ++m) _Pragma("unroll") for (int k = 0; k < 2; ++k) dst[m][k] = *(const LAS bf16x8*)(lds + PG8_SA(b, h) + aoff + m * 2048 + k * 1024); } while (0)
; #define PG8_LDB(dst, b, h) do { _Pragma("unroll") for (int n = 0; n < 2; ++n) _Pragma("unroll") for (int k = 0; k < 2; ++k) dst[n][k] = *(const LAS bf16x8*)(lds + PG8_SB(b, h) + boff + n * 2048 + k * 1024); } while (0)
; #define PG8_MMA(ai, bj, At, Bt) do { __builtin_amdgcn_s_setprio(1); _Pragma("unroll") for (int m = 0; m < 4; ++m) _Pragma("unroll") for (int n = 0; n < 2; ++n) _Pragma("unroll") for (int k = 0; k < 2; ++k) \
;         acc[ai][bj][m][n] = __builtin_amdgcn_mfma_f32_16x16x32_bf16(Bt[n][k], At[m][k], acc[ai][bj][m][n], 0, 0, 0); __builtin_amdgcn_s_setprio(0); } while (0)
; #define PG8_WAIT_V(n) asm volatile("s_waitcnt vmcnt(" #n ")" ::: "memory")
; #define PG8_WAIT_L(n) asm volatile("s_waitcnt lgkmcnt(" #n ")" ::: "memory")
; #define PG8_BAR __builtin_amdgcn_s_barrier()
; template <class Epi>
; __device__ __forceinline__ void gemm_phase(LAS unsigned char* lds, const Gemm g, const StaticOrder& S, const Epi& E) {
;     ...
;         for (int t = 0; t < nt; t += 2) {
;             const bool last = (t == nt - 2);
;             const char* a1 = cA + (size_t)(t + 1) * kstep;
;             const char* a2 = last ? nA : cA + (size_t)(t + 2) * kstep; const char* b2 = last ? nB : cB + (size_t)(t + 2) * kstep;
;             const char* a3 = a2 + kstep; const char* b3 = b2 + kstep;
;             if constexpr (Epi::MIDK > 0) { if (t == Epi::MIDK) E.mid(acc, cur, wr, wc, fr, fq); }
;             PG8_LDB(B0, 0, 0); PG8_LDB(B1, 0, 1); PG8_SCHED; PG8_LDA(At, 0, 0); PG8_STAGE(PG8_SA(1, 1), a1 + hstep, voffA);
;             PG8_WAIT_V(8); PG8_WAIT_L(0); PG8_BAR; PG8_MMA(0, 0, At, B0); PG8_MMA(0, 1, At, B1); PG8_BAR; PG8_SCHED;
;             PG8_LDA(At, 0, 1); PG8_STAGE(PG8_SB(0, 0), b2, voffB); PG8_STAGE(PG8_SB(0, 1), b2 + hstep, voffB); PG8_STAGE(PG8_SA(0, 0), a2, voffA);
;             PG8_WAIT_V(8); PG8_WAIT_L(0); PG8_BAR; PG8_MMA(1, 0, At, B0); PG8_MMA(1, 1, At, B1); PG8_BAR; PG8_SCHED;
.LBB0_971:
	ds_read_b128 v[130:133], v162
	ds_read_b128 v[134:137], v162 offset:1024
	ds_read_b128 v[154:157], v162 offset:2048
	ds_read_b128 v[166:169], v162 offset:3072
	ds_read_b128 v[174:177], v163
	ds_read_b128 v[178:181], v163 offset:1024
	ds_read_b128 v[182:185], v163 offset:2048
	ds_read_b128 v[186:189], v163 offset:3072
	s_add_u32 s24, s22, 0xfff50080
	s_addc_u32 s25, s23, -1
	s_cmp_eq_u32 s59, 40
	s_cselect_b32 s27, s5, s25
	s_cselect_b32 s26, s4, s24
	s_cselect_b32 s25, s21, s58
	s_cselect_b32 s24, s20, s57
	s_add_i32 m0, s39, 0xc000
	ds_read_b128 v[190:193], v164
	ds_read_b128 v[194:197], v164 offset:1024
	ds_read_b128 v[198:201], v164 offset:2048
	ds_read_b128 v[202:205], v164 offset:3072
	ds_read_b128 v[206:209], v164 offset:4096
	ds_read_b128 v[210:213], v164 offset:5120
	ds_read_b128 v[214:217], v164 offset:6144
	ds_read_b128 v[218:221], v164 offset:7168
	global_load_lds_dwordx4 v146, s[22:23]
	s_add_i32 m0, s39, 0xe000
	s_nop 0
	global_load_lds_dwordx4 v148, s[22:23]
	s_waitcnt vmcnt(8)
	s_waitcnt lgkmcnt(0)
	s_setprio 1
	s_barrier
	v_mfma_f32_16x16x32_bf16 v[126:129], v[130:133], v[190:193], v[126:129]
	v_mfma_f32_16x16x32_bf16 v[106:109], v[154:157], v[198:201], v[106:109]
	v_mfma_f32_16x16x32_bf16 v[94:97], v[130:133], v[206:209], v[94:97]
	v_mfma_f32_16x16x32_bf16 v[74:77], v[154:157], v[214:217], v[74:77]
	v_mfma_f32_16x16x32_bf16 v[122:125], v[154:157], v[190:193], v[122:125]
	v_mfma_f32_16x16x32_bf16 v[110:113], v[130:133], v[198:201], v[110:113]
	v_mfma_f32_16x16x32_bf16 v[90:93], v[154:157], v[206:209], v[90:93]
	v_mfma_f32_16x16x32_bf16 v[78:81], v[130:133], v[214:217], v[78:81]
	v_mfma_f32_16x16x32_bf16 v[126:129], v[134:137], v[194:197], v[126:129]
	v_mfma_f32_16x16x32_bf16 v[106:109], v[166:169], v[202:205], v[106:109]
	v_mfma_f32_16x16x32_bf16 v[94:97], v[134:137], v[210:213], v[94:97]
	v_mfma_f32_16x16x32_bf16 v[74:77], v[166:169], v[218:221], v[74:77]
	v_mfma_f32_16x16x32_bf16 v[122:125], v[166:169], v[194:197], v[122:125]
	v_mfma_f32_16x16x32_bf16 v[110:113], v[134:137], v[202:205], v[110:113]
	v_mfma_f32_16x16x32_bf16 v[90:93], v[166:169], v[210:213], v[90:93]
	v_mfma_f32_16x16x32_bf16 v[78:81], v[134:137], v[218:221], v[78:81]
	v_mfma_f32_16x16x32_bf16 v[118:121], v[174:177], v[190:193], v[118:121]
	v_mfma_f32_16x16x32_bf16 v[98:101], v[182:185], v[198:201], v[98:101]
	v_mfma_f32_16x16x32_bf16 v[86:89], v[174:177], v[206:209], v[86:89]
	v_mfma_f32_16x16x32_bf16 v[66:69], v[182:185], v[214:217], v[66:69]
	v_mfma_f32_16x16x32_bf16 v[114:117], v[182:185], v[190:193], v[114:117]
	v_mfma_f32_16x16x32_bf16 v[102:105], v[174:177], v[198:201], v[102:105]
	v_mfma_f32_16x16x32_bf16 v[82:85], v[182:185], v[206:209], v[82:85]
	v_mfma_f32_16x16x32_bf16 v[70:73], v[174:177], v[214:217], v[70:73]
	v_mfma_f32_16x16x32_bf16 v[118:121], v[178:181], v[194:197], v[118:121]
	v_mfma_f32_16x16x32_bf16 v[98:101], v[186:189], v[202:205], v[98:101]
	v_mfma_f32_16x16x32_bf16 v[86:89], v[178:181], v[210:213], v[86:89]
	v_mfma_f32_16x16x32_bf16 v[66:69], v[186:189], v[218:221], v[66:69]
	v_mfma_f32_16x16x32_bf16 v[114:117], v[186:189], v[194:197], v[114:117]
	v_mfma_f32_16x16x32_bf16 v[102:105], v[178:181], v[202:205], v[102:105]
	v_mfma_f32_16x16x32_bf16 v[82:85], v[186:189], v[210:213], v[82:85]
	v_mfma_f32_16x16x32_bf16 v[70:73], v[178:181], v[218:221], v[70:73]
	s_barrier
	s_setprio 0
	s_add_u32 s98, s24, s14
	s_addc_u32 s99, s25, s15
	s_add_u32 s100, s26, s14
	s_addc_u32 s101, s27, s15
	s_add_i32 s60, s51, s38
	s_mov_b32 m0, s60
	ds_read_b128 v[190:193], v164 offset:16384
	ds_read_b128 v[194:197], v164 offset:17408
	ds_read_b128 v[198:201], v164 offset:18432
	ds_read_b128 v[202:205], v164 offset:19456
	ds_read_b128 v[206:209], v164 offset:20480
	ds_read_b128 v[210:213], v164 offset:21504
	ds_read_b128 v[214:217], v164 offset:22528
	ds_read_b128 v[218:221], v164 offset:23552
	global_load_lds_dwordx4 v140, s[24:25]
	s_add_i32 m0, s60, 0x2000
	s_add_u32 s60, s24, 0xb0000
	s_addc_u32 s61, s25, 0
	s_add_i32 s62, s52, s38
	global_load_lds_dwordx4 v144, s[24:25]
	s_mov_b32 m0, s62
	s_nop 0
	global_load_lds_dwordx4 v140, s[60:61]
	s_add_i32 m0, s62, 0x2000
	s_nop 0
	global_load_lds_dwordx4 v144, s[60:61]
	s_mov_b32 m0, s39
	s_nop 0
	global_load_lds_dwordx4 v138, s[26:27]
	s_mov_b32 m0, s40
	s_nop 0
	global_load_lds_dwordx4 v142, s[26:27]
	s_waitcnt vmcnt(8)
	s_waitcnt lgkmcnt(0)
	s_setprio 1
	s_barrier
	v_mfma_f32_16x16x32_bf16 v[62:65], v[130:133], v[190:193], v[62:65]
	v_mfma_f32_16x16x32_bf16 v[42:45], v[154:157], v[198:201], v[42:45]
	v_mfma_f32_16x16x32_bf16 v[30:33], v[130:133], v[206:209], v[30:33]
	v_mfma_f32_16x16x32_bf16 v[10:13], v[154:157], v[214:217], v[10:13]
	v_mfma_f32_16x16x32_bf16 v[58:61], v[154:157], v[190:193], v[58:61]
	v_mfma_f32_16x16x32_bf16 v[46:49], v[130:133], v[198:201], v[46:49]
	v_mfma_f32_16x16x32_bf16 v[26:29], v[154:157], v[206:209], v[26:29]
	v_mfma_f32_16x16x32_bf16 v[14:17], v[130:133], v[214:217], v[14:17]
	v_mfma_f32_16x16x32_bf16 v[62:65], v[134:137], v[194:197], v[62:65]
	v_mfma_f32_16x16x32_bf16 v[42:45], v[166:169], v[202:205], v[42:45]
	v_mfma_f32_16x16x32_bf16 v[30:33], v[134:137], v[210:213], v[30:33]
	v_mfma_f32_16x16x32_bf16 v[10:13], v[166:169], v[218:221], v[10:13]
	v_mfma_f32_16x16x32_bf16 v[58:61], v[166:169], v[194:197], v[58:61]
	v_mfma_f32_16x16x32_bf16 v[46:49], v[134:137], v[202:205], v[46:49]
	v_mfma_f32_16x16x32_bf16 v[26:29], v[166:169], v[210:213], v[26:29]
	v_mfma_f32_16x16x32_bf16 v[14:17], v[134:137], v[218:221], v[14:17]
	v_mfma_f32_16x16x32_bf16 v[54:57], v[174:177], v[190:193], v[54:57]
	v_mfma_f32_16x16x32_bf16 v[34:37], v[182:185], v[198:201], v[34:37]
	v_mfma_f32_16x16x32_bf16 v[22:25], v[174:177], v[206:209], v[22:25]
	v_mfma_f32_16x16x32_bf16 v[2:5], v[182:185], v[214:217], v[2:5]
	v_mfma_f32_16x16x32_bf16 v[50:53], v[182:185], v[190:193], v[50:53]
	v_mfma_f32_16x16x32_bf16 v[38:41], v[174:177], v[198:201], v[38:41]
	v_mfma_f32_16x16x32_bf16 v[18:21], v[182:185], v[206:209], v[18:21]
	v_mfma_f32_16x16x32_bf16 v[6:9], v[174:177], v[214:217], v[6:9]
	v_mfma_f32_16x16x32_bf16 v[54:57], v[178:181], v[194:197], v[54:57]
	v_mfma_f32_16x16x32_bf16 v[34:37], v[186:189], v[202:205], v[34:37]
	v_mfma_f32_16x16x32_bf16 v[22:25], v[178:181], v[210:213], v[22:25]
	v_mfma_f32_16x16x32_bf16 v[2:5], v[186:189], v[218:221], v[2:5]
	v_mfma_f32_16x16x32_bf16 v[50:53], v[186:189], v[194:197], v[50:53]
	v_mfma_f32_16x16x32_bf16 v[38:41], v[178:181], v[202:205], v[38:41]
	v_mfma_f32_16x16x32_bf16 v[18:21], v[186:189], v[210:213], v[18:21]
	v_mfma_f32_16x16x32_bf16 v[6:9], v[178:181], v[218:221], v[6:9]
	s_barrier
; #define PG8_STAGE(bufoff, gbase, voff) do { _Pragma("unroll") for (int _i = 0; _i < 2; ++_i) \
;         __builtin_amdgcn_global_load_lds((const unsigned*)((const char*)(gbase) + (voff)[_i]), (LAS unsigned*)(lds + (bufoff) + ldsw + _i * 8192), 16, 0, 0); } while (0)
; #define PG8_LDA(dst, b, h) do { _Pragma("unroll") for (int m = 0; m < 4; ++m) _Pragma("unroll") for (int k = 0; k < 2; ++k) dst[m][k] = *(const LAS bf16x8*)(lds + PG8_SA(b, h) + aoff + m * 2048 + k * 1024); } while (0)
; #define PG8_LDB(dst, b, h) do { _Pragma("unroll") for (int n = 0; n < 2; ++n) _Pragma("unroll") for (int k = 0; k < 2; ++k) dst[n][k] = *(const LAS bf16x8*)(lds + PG8_SB(b, h) + boff + n * 2048 + k * 1024); } while (0)
; #define PG8_MMA(ai, bj, At, Bt) do { __builtin_amdgcn_s_setprio(1); _Pragma("unroll") for (int m = 0; m < 4; ++m) _Pragma("unroll") for (int n = 0; n < 2; ++n) _Pragma("unroll") for (int k = 0; k < 2; ++k) \
;         acc[ai][bj][m][n] = __builtin_amdgcn_mfma_f32_16x16x32_bf16(Bt[n][k], At[m][k], acc[ai][bj][m][n], 0, 0, 0); __builtin_amdgcn_s_setprio(0); } while (0)
; #define PG8_WAIT_V(n) asm volatile("s_waitcnt vmcnt(" #n ")" ::: "memory")
; #define PG8_WAIT_L(n) asm volatile("s_waitcnt lgkmcnt(" #n ")" ::: "memory")
; #define PG8_BAR __builtin_amdgcn_s_barrier()
; #define PG8_SCHED __builtin_amdgcn_sched_barrier(0)
; template <class Epi>
; __device__ __forceinline__ void gemm_phase(LAS unsigned char* lds, const Gemm g, const StaticOrder& S, const Epi& E) {
;     ...
;             PG8_LDB(B0, 1, 0); PG8_LDB(B1, 1, 1); PG8_SCHED; PG8_LDA(At, 1, 0); PG8_STAGE(PG8_SA(0, 1), a2 + hstep, voffA);
;             PG8_WAIT_V(8); PG8_WAIT_L(0); PG8_BAR; PG8_MMA(0, 0, At, B0); PG8_MMA(0, 1, At, B1); PG8_BAR; PG8_SCHED;
;             PG8_LDA(At, 1, 1); PG8_STAGE(PG8_SB(1, 0), b3, voffB); PG8_STAGE(PG8_SB(1, 1), b3 + hstep, voffB); PG8_STAGE(PG8_SA(1, 0), a3, voffA);
;             PG8_WAIT_V(8); PG8_WAIT_L(0); PG8_BAR; PG8_MMA(1, 0, At, B0); PG8_MMA(1, 1, At, B1); PG8_BAR; PG8_SCHED;
;         }
;         if (wr == 0) PG8_BAR;
	s_setprio 0
	s_add_i32 s60, 0, 0x18000
	s_add_i32 s61, 0, 0x1c000
	v_add_u32_e32 v166, s60, v160
	v_add_u32_e32 v186, s61, v160
	ds_read_b128 v[130:133], v166
	ds_read_b128 v[134:137], v166 offset:1024
	ds_read_b128 v[154:157], v166 offset:2048
	ds_read_b128 v[166:169], v166 offset:3072
	ds_read_b128 v[174:177], v186
	ds_read_b128 v[178:181], v186 offset:1024
	ds_read_b128 v[182:185], v186 offset:2048
	ds_read_b128 v[186:189], v186 offset:3072
	s_add_u32 s26, s26, 0xb0000
	s_addc_u32 s27, s27, 0
	s_mov_b32 m0, s41
	ds_read_b128 v[190:193], v164 offset:32768
	ds_read_b128 v[194:197], v164 offset:33792
	ds_read_b128 v[198:201], v164 offset:34816
	ds_read_b128 v[202:205], v164 offset:35840
	ds_read_b128 v[206:209], v164 offset:36864
	ds_read_b128 v[210:213], v164 offset:37888
	ds_read_b128 v[214:217], v164 offset:38912
	ds_read_b128 v[218:221], v164 offset:39936
	global_load_lds_dwordx4 v138, s[26:27]
	s_mov_b32 m0, s42
	s_nop 0
	global_load_lds_dwordx4 v142, s[26:27]
	s_waitcnt vmcnt(8)
	s_waitcnt lgkmcnt(0)
	s_setprio 1
	s_barrier
	v_mfma_f32_16x16x32_bf16 v[126:129], v[130:133], v[190:193], v[126:129]
	v_mfma_f32_16x16x32_bf16 v[106:109], v[154:157], v[198:201], v[106:109]
	v_mfma_f32_16x16x32_bf16 v[94:97], v[130:133], v[206:209], v[94:97]
	v_mfma_f32_16x16x32_bf16 v[74:77], v[154:157], v[214:217], v[74:77]
	v_mfma_f32_16x16x32_bf16 v[122:125], v[154:157], v[190:193], v[122:125]
	v_mfma_f32_16x16x32_bf16 v[110:113], v[130:133], v[198:201], v[110:113]
	v_mfma_f32_16x16x32_bf16 v[90:93], v[154:157], v[206:209], v[90:93]
	v_mfma_f32_16x16x32_bf16 v[78:81], v[130:133], v[214:217], v[78:81]
	v_mfma_f32_16x16x32_bf16 v[126:129], v[134:137], v[194:197], v[126:129]
	v_mfma_f32_16x16x32_bf16 v[106:109], v[166:169], v[202:205], v[106:109]
	v_mfma_f32_16x16x32_bf16 v[94:97], v[134:137], v[210:213], v[94:97]
	v_mfma_f32_16x16x32_bf16 v[74:77], v[166:169], v[218:221], v[74:77]
	v_mfma_f32_16x16x32_bf16 v[122:125], v[166:169], v[194:197], v[122:125]
	v_mfma_f32_16x16x32_bf16 v[110:113], v[134:137], v[202:205], v[110:113]
	v_mfma_f32_16x16x32_bf16 v[90:93], v[166:169], v[210:213], v[90:93]
	v_mfma_f32_16x16x32_bf16 v[78:81], v[134:137], v[218:221], v[78:81]
	v_mfma_f32_16x16x32_bf16 v[118:121], v[174:177], v[190:193], v[118:121]
	v_mfma_f32_16x16x32_bf16 v[98:101], v[182:185], v[198:201], v[98:101]
	v_mfma_f32_16x16x32_bf16 v[86:89], v[174:177], v[206:209], v[86:89]
	v_mfma_f32_16x16x32_bf16 v[66:69], v[182:185], v[214:217], v[66:69]
	v_mfma_f32_16x16x32_bf16 v[114:117], v[182:185], v[190:193], v[114:117]
	v_mfma_f32_16x16x32_bf16 v[102:105], v[174:177], v[198:201], v[102:105]
	v_mfma_f32_16x16x32_bf16 v[82:85], v[182:185], v[206:209], v[82:85]
	v_mfma_f32_16x16x32_bf16 v[70:73], v[174:177], v[214:217], v[70:73]
	v_mfma_f32_16x16x32_bf16 v[118:121], v[178:181], v[194:197], v[118:121]
	v_mfma_f32_16x16x32_bf16 v[98:101], v[186:189], v[202:205], v[98:101]
	v_mfma_f32_16x16x32_bf16 v[86:89], v[178:181], v[210:213], v[86:89]
	v_mfma_f32_16x16x32_bf16 v[66:69], v[186:189], v[218:221], v[66:69]
	v_mfma_f32_16x16x32_bf16 v[114:117], v[186:189], v[194:197], v[114:117]
	v_mfma_f32_16x16x32_bf16 v[102:105], v[178:181], v[202:205], v[102:105]
	v_mfma_f32_16x16x32_bf16 v[82:85], v[186:189], v[210:213], v[82:85]
	v_mfma_f32_16x16x32_bf16 v[70:73], v[178:181], v[218:221], v[70:73]
	s_barrier
	s_setprio 0
	s_add_i32 s26, s60, s38
	s_mov_b32 m0, s26
	ds_read_b128 v[190:193], v164 offset:49152
	ds_read_b128 v[194:197], v164 offset:50176
	ds_read_b128 v[198:201], v164 offset:51200
	ds_read_b128 v[202:205], v164 offset:52224
	ds_read_b128 v[206:209], v164 offset:53248
	ds_read_b128 v[210:213], v164 offset:54272
	ds_read_b128 v[214:217], v164 offset:55296
	ds_read_b128 v[218:221], v164 offset:56320
	global_load_lds_dwordx4 v140, s[98:99]
	s_add_i32 m0, s26, 0x2000
	s_add_u32 s24, s24, 0xb0080
	s_addc_u32 s25, s25, 0
	s_add_i32 s26, s61, s38
	global_load_lds_dwordx4 v144, s[98:99]
	s_mov_b32 m0, s26
	s_nop 0
	global_load_lds_dwordx4 v140, s[24:25]
	s_add_i32 m0, s26, 0x2000
	s_nop 0
	global_load_lds_dwordx4 v144, s[24:25]
	s_mov_b32 m0, s44
	s_nop 0
	global_load_lds_dwordx4 v138, s[100:101]
	s_mov_b32 m0, s45
	s_nop 0
	global_load_lds_dwordx4 v142, s[100:101]
	s_waitcnt vmcnt(8)
	s_waitcnt lgkmcnt(0)
	s_setprio 1
	s_barrier
	v_mfma_f32_16x16x32_bf16 v[62:65], v[130:133], v[190:193], v[62:65]
	v_mfma_f32_16x16x32_bf16 v[42:45], v[154:157], v[198:201], v[42:45]
	v_mfma_f32_16x16x32_bf16 v[30:33], v[130:133], v[206:209], v[30:33]
	v_mfma_f32_16x16x32_bf16 v[10:13], v[154:157], v[214:217], v[10:13]
	v_mfma_f32_16x16x32_bf16 v[58:61], v[154:157], v[190:193], v[58:61]
	v_mfma_f32_16x16x32_bf16 v[46:49], v[130:133], v[198:201], v[46:49]
	v_mfma_f32_16x16x32_bf16 v[26:29], v[154:157], v[206:209], v[26:29]
	v_mfma_f32_16x16x32_bf16 v[14:17], v[130:133], v[214:217], v[14:17]
	v_mfma_f32_16x16x32_bf16 v[62:65], v[134:137], v[194:197], v[62:65]
	v_mfma_f32_16x16x32_bf16 v[42:45], v[166:169], v[202:205], v[42:45]
	v_mfma_f32_16x16x32_bf16 v[30:33], v[134:137], v[210:213], v[30:33]
	v_mfma_f32_16x16x32_bf16 v[10:13], v[166:169], v[218:221], v[10:13]
	v_mfma_f32_16x16x32_bf16 v[58:61], v[166:169], v[194:197], v[58:61]
	v_mfma_f32_16x16x32_bf16 v[46:49], v[134:137], v[202:205], v[46:49]
	v_mfma_f32_16x16x32_bf16 v[26:29], v[166:169], v[210:213], v[26:29]
	v_mfma_f32_16x16x32_bf16 v[14:17], v[134:137], v[218:221], v[14:17]
	v_mfma_f32_16x16x32_bf16 v[54:57], v[174:177], v[190:193], v[54:57]
	v_mfma_f32_16x16x32_bf16 v[34:37], v[182:185], v[198:201], v[34:37]
	v_mfma_f32_16x16x32_bf16 v[22:25], v[174:177], v[206:209], v[22:25]
	v_mfma_f32_16x16x32_bf16 v[2:5], v[182:185], v[214:217], v[2:5]
	v_mfma_f32_16x16x32_bf16 v[50:53], v[182:185], v[190:193], v[50:53]
	v_mfma_f32_16x16x32_bf16 v[38:41], v[174:177], v[198:201], v[38:41]
	v_mfma_f32_16x16x32_bf16 v[18:21], v[182:185], v[206:209], v[18:21]
	v_mfma_f32_16x16x32_bf16 v[6:9], v[174:177], v[214:217], v[6:9]
	v_mfma_f32_16x16x32_bf16 v[54:57], v[178:181], v[194:197], v[54:57]
	v_mfma_f32_16x16x32_bf16 v[34:37], v[186:189], v[202:205], v[34:37]
	v_mfma_f32_16x16x32_bf16 v[22:25], v[178:181], v[210:213], v[22:25]
	v_mfma_f32_16x16x32_bf16 v[2:5], v[186:189], v[218:221], v[2:5]
	v_mfma_f32_16x16x32_bf16 v[50:53], v[186:189], v[194:197], v[50:53]
	v_mfma_f32_16x16x32_bf16 v[38:41], v[178:181], v[202:205], v[38:41]
	v_mfma_f32_16x16x32_bf16 v[18:21], v[186:189], v[210:213], v[18:21]
	v_mfma_f32_16x16x32_bf16 v[6:9], v[178:181], v[218:221], v[6:9]
	s_barrier
	s_setprio 0
	s_add_i32 s59, s59, 2
	s_add_u32 s22, s22, 0x100
	s_addc_u32 s23, s23, 0
	s_add_u32 s57, s57, 0x100
	s_addc_u32 s58, s58, 0
	s_cmp_gt_u32 s59, 41
	s_cbranch_scc0 .LBB0_971
	s_and_b64 vcc, exec, s[18:19]
	s_cbranch_vccz .LBB0_974
	s_barrier
